# GEMM K-loops: accumulator zero-init moved from the unit preheader into the first K-iteration, after the first tile loads are issued (overlaps their latency)
# speedup vs baseline: 1.0021x; 1.0021x over previous
; #define PG8_STAGE(bufoff, gbase, voff) do { _Pragma("unroll") for (int _i = 0; _i < 2; ++_i) \
;         __builtin_amdgcn_global_load_lds((const unsigned*)((const char*)(gbase) + (voff)[_i]), (LAS unsigned*)(lds + (bufoff) + ldsw + _i * 8192), 16, 0, 0); } while (0)
; #define PG8_LDA(dst, b, h) do { _Pragma("unroll") for (int m = 0; m < 4; ++m) _Pragma("unroll") for (int k = 0; k < 2; ++k) dst[m][k] = *(const LAS bf16x8*)(lds + PG8_SA(b, h) + aoff + m * 2048 + k * 1024); } while (0)
; #define PG8_LDB(dst, b, h) do { _Pragma("unroll") for (int n = 0; n < 2; ++n) _Pragma("unroll") for (int k = 0; k < 2; ++k) dst[n][k] = *(const LAS bf16x8*)(lds + PG8_SB(b, h) + boff + n * 2048 + k * 1024); } while (0)
; #define PG8_MMA(ai, bj, At, Bt) do { __builtin_amdgcn_s_setprio(1); _Pragma("unroll") for (int m = 0; m < 4; ++m) _Pragma("unroll") for (int n = 0; n < 2; ++n) _Pragma("unroll") for (int k = 0; k < 2; ++k) \
;         acc[ai][bj][m][n] = __builtin_amdgcn_mfma_f32_16x16x32_bf16(Bt[n][k], At[m][k], acc[ai][bj][m][n], 0, 0, 0); __builtin_amdgcn_s_setprio(0); } while (0)
; #define PG8_WAIT_V(n) asm volatile("s_waitcnt vmcnt(" #n ")" ::: "memory")
; #define PG8_WAIT_L(n) asm volatile("s_waitcnt lgkmcnt(" #n ")" ::: "memory")
; #define PG8_BAR __builtin_amdgcn_s_barrier()
; template <class Epi, class Sched, bool ALIGN_EPI>
; __device__ __forceinline__ void gemm_phase(LAS unsigned char* lds, const Gemm g, const Sched& S, const Epi& E, int wave_s) {
;     ...
;         for (int t = 0; t < nt; t += 2) {
;             const bool last = (t == nt - 2);
;             const char* a1 = cA + (size_t)(t + 1) * kstep;
;             const char* a2 = last ? nA : cA + (size_t)(t + 2) * kstep; const char* b2 = last ? nB : cB + (size_t)(t + 2) * kstep;
;             const char* a3 = a2 + kstep; const char* b3 = b2 + kstep;
;             PG8_LDB(B0, 0, 0); PG8_LDB(B1, 0, 1); PG8_SCHED; PG8_LDA(At, 0, 0); PG8_STAGE(PG8_SA(1, 1), a1 + hstepA, voffA);
;             PG8_WAIT_V(8); PG8_WAIT_L(0); PG8_BAR; PG8_MMA(0, 0, At, B0); PG8_MMA(0, 1, At, B1); PG8_BAR; PG8_SCHED;
;     ...
; #pragma unroll
;         for (int a = 0; a < 2; ++a)
; #pragma unroll
;             for (int b = 0; b < 2; ++b)
; #pragma unroll
;                 for (int m = 0; m < 4; ++m)
; #pragma unroll
;                     for (int n = 0; n < 2; ++n) acc[a][b][m][n] = (f32x4){0.f, 0.f, 0.f, 0.f};
.LBB0_259:
	s_add_u32 s6, s4, 0xfffc0080
	s_addc_u32 s7, s5, -1
	s_add_i32 s47, 0, 0x10000
	s_cmp_eq_u32 s46, 12
	s_cselect_b32 s9, s21, s7
	s_cselect_b32 s8, s28, s6
	s_cselect_b32 s7, s19, s31
	s_cselect_b32 s6, s29, s30
	s_add_i32 s50, 0, 0x14000
	v_add_u32_e32 v62, s47, v1
	v_add_u32_e32 v170, s50, v1
	ds_read_b128 v[42:45], v62
	ds_read_b128 v[46:49], v62 offset:1024
	ds_read_b128 v[58:61], v62 offset:2048
	ds_read_b128 v[62:65], v62 offset:3072
	ds_read_b128 v[158:161], v170
	ds_read_b128 v[162:165], v170 offset:1024
	ds_read_b128 v[166:169], v170 offset:2048
	ds_read_b128 v[174:177], v170 offset:3072
	v_lshl_add_u64 v[170:171], s[4:5], 0, v[154:155]
	s_add_i32 m0, s35, 0xc000
	ds_read_b128 v[178:181], v172
	ds_read_b128 v[182:185], v172 offset:1024
	ds_read_b128 v[186:189], v172 offset:2048
	ds_read_b128 v[190:193], v172 offset:3072
	ds_read_b128 v[194:197], v172 offset:4096
	ds_read_b128 v[198:201], v172 offset:5120
	ds_read_b128 v[202:205], v172 offset:6144
	ds_read_b128 v[206:209], v172 offset:7168
	global_load_lds_dwordx4 v[170:171], off
	v_lshl_add_u64 v[170:171], s[4:5], 0, v[156:157]
	s_add_i32 m0, s35, 0xe000
	s_nop 0
	global_load_lds_dwordx4 v[170:171], off
	s_cmp_lg_u32 s46, -2
	s_cbranch_scc1 .Lzacc_259_skip
	v_mov_b32_e32 v3, 0
	v_mov_b32_e32 v4, 0
	v_mov_b32_e32 v5, 0
	v_mov_b32_e32 v6, 0
	v_mov_b32_e32 v7, 0
	v_mov_b32_e32 v8, 0
	v_mov_b32_e32 v9, 0
	v_mov_b32_e32 v18, 0
	v_mov_b32_e32 v19, 0
	v_mov_b32_e32 v20, 0
	v_mov_b32_e32 v21, 0
	v_mov_b32_e32 v22, 0
	v_mov_b32_e32 v23, 0
	v_mov_b32_e32 v24, 0
	v_mov_b32_e32 v25, 0
	v_mov_b32_e32 v34, 0
	v_mov_b32_e32 v35, 0
	v_mov_b32_e32 v36, 0
	v_mov_b32_e32 v37, 0
	v_mov_b32_e32 v38, 0
	v_mov_b32_e32 v39, 0
	v_mov_b32_e32 v40, 0
	v_mov_b32_e32 v41, 0
	v_mov_b32_e32 v66, 0
	v_mov_b32_e32 v67, 0
	v_mov_b32_e32 v68, 0
	v_mov_b32_e32 v69, 0
	v_mov_b32_e32 v70, 0
	v_mov_b32_e32 v71, 0
	v_mov_b32_e32 v72, 0
	v_mov_b32_e32 v73, 0
	v_mov_b32_e32 v10, 0
	v_mov_b32_e32 v11, 0
	v_mov_b32_e32 v12, 0
	v_mov_b32_e32 v13, 0
	v_mov_b32_e32 v14, 0
	v_mov_b32_e32 v15, 0
	v_mov_b32_e32 v16, 0
	v_mov_b32_e32 v17, 0
	v_mov_b32_e32 v26, 0
	v_mov_b32_e32 v27, 0
	v_mov_b32_e32 v28, 0
	v_mov_b32_e32 v29, 0
	v_mov_b32_e32 v30, 0
	v_mov_b32_e32 v31, 0
	v_mov_b32_e32 v32, 0
	v_mov_b32_e32 v33, 0
	v_mov_b32_e32 v50, 0
	v_mov_b32_e32 v51, 0
	v_mov_b32_e32 v52, 0
	v_mov_b32_e32 v53, 0
	v_mov_b32_e32 v54, 0
	v_mov_b32_e32 v55, 0
	v_mov_b32_e32 v56, 0
	v_mov_b32_e32 v57, 0
	v_mov_b32_e32 v74, 0
	v_mov_b32_e32 v75, 0
	v_mov_b32_e32 v76, 0
	v_mov_b32_e32 v77, 0
	v_mov_b32_e32 v78, 0
	v_mov_b32_e32 v79, 0
	v_mov_b32_e32 v80, 0
	v_mov_b32_e32 v81, 0
	v_mov_b32_e32 v82, 0
	v_mov_b32_e32 v83, 0
	v_mov_b32_e32 v84, 0
	v_mov_b32_e32 v85, 0
	v_mov_b32_e32 v86, 0
	v_mov_b32_e32 v87, 0
	v_mov_b32_e32 v88, 0
	v_mov_b32_e32 v89, 0
	v_mov_b32_e32 v98, 0
	v_mov_b32_e32 v99, 0
	v_mov_b32_e32 v100, 0
	v_mov_b32_e32 v101, 0
	v_mov_b32_e32 v102, 0
	v_mov_b32_e32 v103, 0
	v_mov_b32_e32 v104, 0
	v_mov_b32_e32 v105, 0
	v_mov_b32_e32 v114, 0
	v_mov_b32_e32 v115, 0
	v_mov_b32_e32 v116, 0
	v_mov_b32_e32 v117, 0
	v_mov_b32_e32 v118, 0
	v_mov_b32_e32 v119, 0
	v_mov_b32_e32 v120, 0
	v_mov_b32_e32 v121, 0
	v_mov_b32_e32 v130, 0
	v_mov_b32_e32 v131, 0
	v_mov_b32_e32 v132, 0
	v_mov_b32_e32 v133, 0
	v_mov_b32_e32 v134, 0
	v_mov_b32_e32 v135, 0
	v_mov_b32_e32 v136, 0
	v_mov_b32_e32 v137, 0
	v_mov_b32_e32 v90, 0
	v_mov_b32_e32 v91, 0
	v_mov_b32_e32 v92, 0
	v_mov_b32_e32 v93, 0
	v_mov_b32_e32 v94, 0
	v_mov_b32_e32 v95, 0
	v_mov_b32_e32 v96, 0
	v_mov_b32_e32 v97, 0
	v_mov_b32_e32 v106, 0
	v_mov_b32_e32 v107, 0
	v_mov_b32_e32 v108, 0
	v_mov_b32_e32 v109, 0
	v_mov_b32_e32 v110, 0
	v_mov_b32_e32 v111, 0
	v_mov_b32_e32 v112, 0
	v_mov_b32_e32 v113, 0
	v_mov_b32_e32 v122, 0
	v_mov_b32_e32 v123, 0
	v_mov_b32_e32 v124, 0
	v_mov_b32_e32 v125, 0
	v_mov_b32_e32 v126, 0
	v_mov_b32_e32 v127, 0
	v_mov_b32_e32 v128, 0
	v_mov_b32_e32 v129, 0
	v_mov_b32_e32 v138, 0
	v_mov_b32_e32 v139, 0
	v_mov_b32_e32 v140, 0
	v_mov_b32_e32 v141, 0
	v_mov_b32_e32 v142, 0
	v_mov_b32_e32 v143, 0
	v_mov_b32_e32 v144, 0
	v_mov_b32_e32 v145, 0
.Lzacc_259_skip:
	s_waitcnt vmcnt(8)
	s_waitcnt lgkmcnt(0)
	s_barrier
	s_setprio 1
	s_waitcnt lgkmcnt(0)
	v_mfma_f32_16x16x32_bf16 v[142:145], v[42:45], v[178:181], v[142:145]
	v_mfma_f32_16x16x32_bf16 v[138:141], v[58:61], v[178:181], v[138:141]
	v_mfma_f32_16x16x32_bf16 v[126:129], v[42:45], v[186:189], v[126:129]
	v_mfma_f32_16x16x32_bf16 v[122:125], v[58:61], v[186:189], v[122:125]
	v_mfma_f32_16x16x32_bf16 v[110:113], v[42:45], v[194:197], v[110:113]
	v_mfma_f32_16x16x32_bf16 v[106:109], v[58:61], v[194:197], v[106:109]
	v_mfma_f32_16x16x32_bf16 v[94:97], v[42:45], v[202:205], v[94:97]
	v_mfma_f32_16x16x32_bf16 v[90:93], v[58:61], v[202:205], v[90:93]
	v_mfma_f32_16x16x32_bf16 v[142:145], v[46:49], v[182:185], v[142:145]
	v_mfma_f32_16x16x32_bf16 v[138:141], v[62:65], v[182:185], v[138:141]
	v_mfma_f32_16x16x32_bf16 v[126:129], v[46:49], v[190:193], v[126:129]
	v_mfma_f32_16x16x32_bf16 v[122:125], v[62:65], v[190:193], v[122:125]
	v_mfma_f32_16x16x32_bf16 v[110:113], v[46:49], v[198:201], v[110:113]
	v_mfma_f32_16x16x32_bf16 v[106:109], v[62:65], v[198:201], v[106:109]
	v_mfma_f32_16x16x32_bf16 v[94:97], v[46:49], v[206:209], v[94:97]
	v_mfma_f32_16x16x32_bf16 v[90:93], v[62:65], v[206:209], v[90:93]
	s_setprio 0
	s_setprio 1
	v_mfma_f32_16x16x32_bf16 v[134:137], v[158:161], v[178:181], v[134:137]
	v_mfma_f32_16x16x32_bf16 v[130:133], v[166:169], v[178:181], v[130:133]
	v_mfma_f32_16x16x32_bf16 v[118:121], v[158:161], v[186:189], v[118:121]
	v_mfma_f32_16x16x32_bf16 v[114:117], v[166:169], v[186:189], v[114:117]
	v_mfma_f32_16x16x32_bf16 v[102:105], v[158:161], v[194:197], v[102:105]
	v_mfma_f32_16x16x32_bf16 v[98:101], v[166:169], v[194:197], v[98:101]
	v_mfma_f32_16x16x32_bf16 v[86:89], v[158:161], v[202:205], v[86:89]
	v_mfma_f32_16x16x32_bf16 v[82:85], v[166:169], v[202:205], v[82:85]
	v_mfma_f32_16x16x32_bf16 v[134:137], v[162:165], v[182:185], v[134:137]
	v_mfma_f32_16x16x32_bf16 v[130:133], v[174:177], v[182:185], v[130:133]
	v_mfma_f32_16x16x32_bf16 v[118:121], v[162:165], v[190:193], v[118:121]
	v_mfma_f32_16x16x32_bf16 v[114:117], v[174:177], v[190:193], v[114:117]
	v_mfma_f32_16x16x32_bf16 v[102:105], v[162:165], v[198:201], v[102:105]
	v_mfma_f32_16x16x32_bf16 v[98:101], v[174:177], v[198:201], v[98:101]
	v_mfma_f32_16x16x32_bf16 v[86:89], v[162:165], v[206:209], v[86:89]
	v_mfma_f32_16x16x32_bf16 v[82:85], v[174:177], v[206:209], v[82:85]
	s_setprio 0
	s_barrier
; #define PG8_STAGE(bufoff, gbase, voff) do { _Pragma("unroll") for (int _i = 0; _i < 2; ++_i) \
;         __builtin_amdgcn_global_load_lds((const unsigned*)((const char*)(gbase) + (voff)[_i]), (LAS unsigned*)(lds + (bufoff) + ldsw + _i * 8192), 16, 0, 0); } while (0)
; #define PG8_LDA(dst, b, h) do { _Pragma("unroll") for (int m = 0; m < 4; ++m) _Pragma("unroll") for (int k = 0; k < 2; ++k) dst[m][k] = *(const LAS bf16x8*)(lds + PG8_SA(b, h) + aoff + m * 2048 + k * 1024); } while (0)
; #define PG8_LDB(dst, b, h) do { _Pragma("unroll") for (int n = 0; n < 2; ++n) _Pragma("unroll") for (int k = 0; k < 2; ++k) dst[n][k] = *(const LAS bf16x8*)(lds + PG8_SB(b, h) + boff + n * 2048 + k * 1024); } while (0)
; #define PG8_MMA(ai, bj, At, Bt) do { __builtin_amdgcn_s_setprio(1); _Pragma("unroll") for (int m = 0; m < 4; ++m) _Pragma("unroll") for (int n = 0; n < 2; ++n) _Pragma("unroll") for (int k = 0; k < 2; ++k) \
;         acc[ai][bj][m][n] = __builtin_amdgcn_mfma_f32_16x16x32_bf16(Bt[n][k], At[m][k], acc[ai][bj][m][n], 0, 0, 0); __builtin_amdgcn_s_setprio(0); } while (0)
; #define PG8_WAIT_V(n) asm volatile("s_waitcnt vmcnt(" #n ")" ::: "memory")
; #define PG8_WAIT_L(n) asm volatile("s_waitcnt lgkmcnt(" #n ")" ::: "memory")
; #define PG8_BAR __builtin_amdgcn_s_barrier()
; #define PG8_SCHED __builtin_amdgcn_sched_barrier(0)
; template <class Epi, class Sched, bool ALIGN_EPI>
; __device__ __forceinline__ void gemm_phase(LAS unsigned char* lds, const Gemm g, const Sched& S, const Epi& E, int wave_s) {
;     ...
;             PG8_LDA(At, 0, 1); PG8_STAGE(PG8_SB(0, 0), b2, voffB); PG8_STAGE(PG8_SB(0, 1), b2 + hstepB, voffB); PG8_STAGE(PG8_SA(0, 0), a2, voffA);
;             PG8_WAIT_V(8); PG8_WAIT_L(0); PG8_BAR; PG8_MMA(1, 0, At, B0); PG8_MMA(1, 1, At, B1); PG8_BAR; PG8_SCHED;
;             PG8_LDB(B0, 1, 0); PG8_LDB(B1, 1, 1); PG8_SCHED; PG8_LDA(At, 1, 0); PG8_STAGE(PG8_SA(0, 1), a2 + hstepA, voffA);
;             PG8_WAIT_V(8); PG8_WAIT_L(0); PG8_BAR; PG8_MMA(0, 0, At, B0); PG8_MMA(0, 1, At, B1); PG8_BAR; PG8_SCHED;
	s_add_i32 s47, s47, s34
	v_lshl_add_u64 v[170:171], s[6:7], 0, v[150:151]
	s_mov_b32 m0, s47
	ds_read_b128 v[178:181], v172 offset:16384
	ds_read_b128 v[182:185], v172 offset:17408
	ds_read_b128 v[186:189], v172 offset:18432
	ds_read_b128 v[190:193], v172 offset:19456
	ds_read_b128 v[194:197], v172 offset:20480
	ds_read_b128 v[198:201], v172 offset:21504
	ds_read_b128 v[202:205], v172 offset:22528
	ds_read_b128 v[206:209], v172 offset:23552
	global_load_lds_dwordx4 v[170:171], off
	s_add_i32 m0, s47, 0x2000
	s_add_u32 s48, s6, 0x40000
	v_lshl_add_u64 v[210:211], s[6:7], 0, v[146:147]
	s_addc_u32 s49, s7, 0
	s_add_i32 s47, s50, s34
	global_load_lds_dwordx4 v[210:211], off
	v_lshl_add_u64 v[212:213], s[48:49], 0, v[150:151]
	s_mov_b32 m0, s47
	v_lshl_add_u64 v[214:215], s[8:9], 0, v[148:149]
	global_load_lds_dwordx4 v[212:213], off
	v_lshl_add_u64 v[212:213], s[48:49], 0, v[146:147]
	s_add_i32 m0, s47, 0x2000
	s_nop 0
	global_load_lds_dwordx4 v[212:213], off
	v_lshl_add_u64 v[212:213], s[8:9], 0, v[152:153]
	s_mov_b32 m0, s35
	s_nop 0
	global_load_lds_dwordx4 v[212:213], off
	s_mov_b32 m0, s36
	s_nop 0
	global_load_lds_dwordx4 v[214:215], off
	s_waitcnt vmcnt(8)
	s_waitcnt lgkmcnt(0)
	s_barrier
	s_setprio 1
	s_waitcnt lgkmcnt(0)
	v_mfma_f32_16x16x32_bf16 v[78:81], v[42:45], v[178:181], v[78:81]
	v_mfma_f32_16x16x32_bf16 v[74:77], v[58:61], v[178:181], v[74:77]
	v_mfma_f32_16x16x32_bf16 v[54:57], v[42:45], v[186:189], v[54:57]
	v_mfma_f32_16x16x32_bf16 v[50:53], v[58:61], v[186:189], v[50:53]
	v_mfma_f32_16x16x32_bf16 v[30:33], v[42:45], v[194:197], v[30:33]
	v_mfma_f32_16x16x32_bf16 v[26:29], v[58:61], v[194:197], v[26:29]
	v_mfma_f32_16x16x32_bf16 v[14:17], v[42:45], v[202:205], v[14:17]
	v_mfma_f32_16x16x32_bf16 v[10:13], v[58:61], v[202:205], v[10:13]
	v_mfma_f32_16x16x32_bf16 v[78:81], v[46:49], v[182:185], v[78:81]
	v_mfma_f32_16x16x32_bf16 v[74:77], v[62:65], v[182:185], v[74:77]
	v_mfma_f32_16x16x32_bf16 v[54:57], v[46:49], v[190:193], v[54:57]
	v_mfma_f32_16x16x32_bf16 v[50:53], v[62:65], v[190:193], v[50:53]
	v_mfma_f32_16x16x32_bf16 v[30:33], v[46:49], v[198:201], v[30:33]
	v_mfma_f32_16x16x32_bf16 v[26:29], v[62:65], v[198:201], v[26:29]
	v_mfma_f32_16x16x32_bf16 v[14:17], v[46:49], v[206:209], v[14:17]
	v_mfma_f32_16x16x32_bf16 v[10:13], v[62:65], v[206:209], v[10:13]
	s_setprio 0
	s_setprio 1
	v_mfma_f32_16x16x32_bf16 v[38:41], v[158:161], v[186:189], v[38:41]
	v_mfma_f32_16x16x32_bf16 v[34:37], v[166:169], v[186:189], v[34:37]
	v_mfma_f32_16x16x32_bf16 v[22:25], v[158:161], v[194:197], v[22:25]
	v_mfma_f32_16x16x32_bf16 v[18:21], v[166:169], v[194:197], v[18:21]
	v_mfma_f32_16x16x32_bf16 v[6:9], v[158:161], v[202:205], v[6:9]
	v_mfma_f32_16x16x32_bf16 v[2:5], v[166:169], v[202:205], v[2:5]
	v_mfma_f32_16x16x32_bf16 v[42:45], v[158:161], v[178:181], v[70:73]
	v_mfma_f32_16x16x32_bf16 v[46:49], v[166:169], v[178:181], v[66:69]
	v_mfma_f32_16x16x32_bf16 v[38:41], v[162:165], v[190:193], v[38:41]
	v_mfma_f32_16x16x32_bf16 v[34:37], v[174:177], v[190:193], v[34:37]
	v_mfma_f32_16x16x32_bf16 v[22:25], v[162:165], v[198:201], v[22:25]
	v_mfma_f32_16x16x32_bf16 v[18:21], v[174:177], v[198:201], v[18:21]
	v_mfma_f32_16x16x32_bf16 v[6:9], v[162:165], v[206:209], v[6:9]
	v_mfma_f32_16x16x32_bf16 v[2:5], v[174:177], v[206:209], v[2:5]
	v_mfma_f32_16x16x32_bf16 v[42:45], v[162:165], v[182:185], v[42:45]
	v_mfma_f32_16x16x32_bf16 v[46:49], v[174:177], v[182:185], v[46:49]
	s_setprio 0
	s_barrier
	s_add_i32 s47, 0, 0x18000
	s_add_i32 s48, 0, 0x1c000
	v_add_u32_e32 v70, s47, v1
	v_add_u32_e32 v173, s48, v1
	ds_read_b128 v[58:61], v70
	ds_read_b128 v[62:65], v70 offset:1024
	ds_read_b128 v[66:69], v70 offset:2048
	ds_read_b128 v[70:73], v70 offset:3072
	ds_read_b128 v[158:161], v173
	ds_read_b128 v[162:165], v173 offset:1024
	ds_read_b128 v[166:169], v173 offset:2048
	ds_read_b128 v[174:177], v173 offset:3072
	s_add_u32 s8, s8, 0x40000
	s_addc_u32 s9, s9, 0
	s_mov_b32 m0, s37
	v_lshl_add_u64 v[216:217], s[8:9], 0, v[152:153]
	ds_read_b128 v[178:181], v172 offset:32768
	ds_read_b128 v[182:185], v172 offset:33792
	ds_read_b128 v[186:189], v172 offset:34816
	ds_read_b128 v[190:193], v172 offset:35840
	ds_read_b128 v[194:197], v172 offset:36864
	ds_read_b128 v[198:201], v172 offset:37888
	ds_read_b128 v[202:205], v172 offset:38912
	ds_read_b128 v[206:209], v172 offset:39936
	global_load_lds_dwordx4 v[216:217], off
	v_lshl_add_u64 v[216:217], s[8:9], 0, v[148:149]
	s_mov_b32 m0, s38
	s_nop 0
	global_load_lds_dwordx4 v[216:217], off
	s_waitcnt vmcnt(8)
	s_waitcnt lgkmcnt(0)
	s_barrier
; #define PG8_STAGE(bufoff, gbase, voff) do { _Pragma("unroll") for (int _i = 0; _i < 2; ++_i) \
;         __builtin_amdgcn_global_load_lds((const unsigned*)((const char*)(gbase) + (voff)[_i]), (LAS unsigned*)(lds + (bufoff) + ldsw + _i * 8192), 16, 0, 0); } while (0)
; #define PG8_LDA(dst, b, h) do { _Pragma("unroll") for (int m = 0; m < 4; ++m) _Pragma("unroll") for (int k = 0; k < 2; ++k) dst[m][k] = *(const LAS bf16x8*)(lds + PG8_SA(b, h) + aoff + m * 2048 + k * 1024); } while (0)
; #define PG8_MMA(ai, bj, At, Bt) do { __builtin_amdgcn_s_setprio(1); _Pragma("unroll") for (int m = 0; m < 4; ++m) _Pragma("unroll") for (int n = 0; n < 2; ++n) _Pragma("unroll") for (int k = 0; k < 2; ++k) \
;         acc[ai][bj][m][n] = __builtin_amdgcn_mfma_f32_16x16x32_bf16(Bt[n][k], At[m][k], acc[ai][bj][m][n], 0, 0, 0); __builtin_amdgcn_s_setprio(0); } while (0)
; #define PG8_WAIT_V(n) asm volatile("s_waitcnt vmcnt(" #n ")" ::: "memory")
; #define PG8_WAIT_L(n) asm volatile("s_waitcnt lgkmcnt(" #n ")" ::: "memory")
; #define PG8_BAR __builtin_amdgcn_s_barrier()
; #define PG8_SCHED __builtin_amdgcn_sched_barrier(0)
; template <class Epi, class Sched, bool ALIGN_EPI>
; __device__ __forceinline__ void gemm_phase(LAS unsigned char* lds, const Gemm g, const Sched& S, const Epi& E, int wave_s) {
;     ...
;             PG8_WAIT_V(8); PG8_WAIT_L(0); PG8_BAR; PG8_MMA(0, 0, At, B0); PG8_MMA(0, 1, At, B1); PG8_BAR; PG8_SCHED;
;             PG8_LDA(At, 1, 1); PG8_STAGE(PG8_SB(1, 0), b3, voffB); PG8_STAGE(PG8_SB(1, 1), b3 + hstepB, voffB); PG8_STAGE(PG8_SA(1, 0), a3, voffA);
;             PG8_WAIT_V(8); PG8_WAIT_L(0); PG8_BAR; PG8_MMA(1, 0, At, B0); PG8_MMA(1, 1, At, B1); PG8_BAR; PG8_SCHED;
;         }
;         if constexpr (ALIGN_EPI) { if (wr == 0) PG8_BAR; }
;         E(acc, cur, wr, wc, fr, fq);
;         if (!has_next) break;
	s_setprio 1
	s_waitcnt lgkmcnt(0)
	v_mfma_f32_16x16x32_bf16 v[142:145], v[58:61], v[178:181], v[142:145]
	v_mfma_f32_16x16x32_bf16 v[138:141], v[66:69], v[178:181], v[138:141]
	v_mfma_f32_16x16x32_bf16 v[126:129], v[58:61], v[186:189], v[126:129]
	v_mfma_f32_16x16x32_bf16 v[122:125], v[66:69], v[186:189], v[122:125]
	v_mfma_f32_16x16x32_bf16 v[110:113], v[58:61], v[194:197], v[110:113]
	v_mfma_f32_16x16x32_bf16 v[106:109], v[66:69], v[194:197], v[106:109]
	v_mfma_f32_16x16x32_bf16 v[94:97], v[58:61], v[202:205], v[94:97]
	v_mfma_f32_16x16x32_bf16 v[90:93], v[66:69], v[202:205], v[90:93]
	v_mfma_f32_16x16x32_bf16 v[142:145], v[62:65], v[182:185], v[142:145]
	v_mfma_f32_16x16x32_bf16 v[138:141], v[70:73], v[182:185], v[138:141]
	v_mfma_f32_16x16x32_bf16 v[126:129], v[62:65], v[190:193], v[126:129]
	v_mfma_f32_16x16x32_bf16 v[122:125], v[70:73], v[190:193], v[122:125]
	v_mfma_f32_16x16x32_bf16 v[110:113], v[62:65], v[198:201], v[110:113]
	v_mfma_f32_16x16x32_bf16 v[106:109], v[70:73], v[198:201], v[106:109]
	v_mfma_f32_16x16x32_bf16 v[94:97], v[62:65], v[206:209], v[94:97]
	v_mfma_f32_16x16x32_bf16 v[90:93], v[70:73], v[206:209], v[90:93]
	s_setprio 0
	s_setprio 1
	v_mfma_f32_16x16x32_bf16 v[134:137], v[158:161], v[178:181], v[134:137]
	v_mfma_f32_16x16x32_bf16 v[130:133], v[166:169], v[178:181], v[130:133]
	v_mfma_f32_16x16x32_bf16 v[118:121], v[158:161], v[186:189], v[118:121]
	v_mfma_f32_16x16x32_bf16 v[114:117], v[166:169], v[186:189], v[114:117]
	v_mfma_f32_16x16x32_bf16 v[102:105], v[158:161], v[194:197], v[102:105]
	v_mfma_f32_16x16x32_bf16 v[98:101], v[166:169], v[194:197], v[98:101]
	v_mfma_f32_16x16x32_bf16 v[86:89], v[158:161], v[202:205], v[86:89]
	v_mfma_f32_16x16x32_bf16 v[82:85], v[166:169], v[202:205], v[82:85]
	v_mfma_f32_16x16x32_bf16 v[134:137], v[162:165], v[182:185], v[134:137]
	v_mfma_f32_16x16x32_bf16 v[130:133], v[174:177], v[182:185], v[130:133]
	v_mfma_f32_16x16x32_bf16 v[118:121], v[162:165], v[190:193], v[118:121]
	v_mfma_f32_16x16x32_bf16 v[114:117], v[174:177], v[190:193], v[114:117]
	v_mfma_f32_16x16x32_bf16 v[102:105], v[162:165], v[198:201], v[102:105]
	v_mfma_f32_16x16x32_bf16 v[98:101], v[174:177], v[198:201], v[98:101]
	v_mfma_f32_16x16x32_bf16 v[86:89], v[162:165], v[206:209], v[86:89]
	v_mfma_f32_16x16x32_bf16 v[82:85], v[174:177], v[206:209], v[82:85]
	s_setprio 0
	s_barrier
	s_add_i32 s8, s47, s34
	v_lshl_add_u64 v[170:171], v[170:171], 0, s[74:75]
	s_mov_b32 m0, s8
	ds_read_b128 v[178:181], v172 offset:49152
	ds_read_b128 v[182:185], v172 offset:50176
	ds_read_b128 v[186:189], v172 offset:51200
	ds_read_b128 v[190:193], v172 offset:52224
	ds_read_b128 v[194:197], v172 offset:53248
	ds_read_b128 v[198:201], v172 offset:54272
	ds_read_b128 v[202:205], v172 offset:55296
	ds_read_b128 v[206:209], v172 offset:56320
	global_load_lds_dwordx4 v[170:171], off
	s_add_i32 m0, s8, 0x2000
	s_add_u32 s6, s6, 0x40080
	v_lshl_add_u64 v[170:171], v[210:211], 0, s[74:75]
	s_addc_u32 s7, s7, 0
	s_add_i32 s8, s48, s34
	global_load_lds_dwordx4 v[170:171], off
	v_lshl_add_u64 v[170:171], s[6:7], 0, v[150:151]
	s_mov_b32 m0, s8
	s_nop 0
	global_load_lds_dwordx4 v[170:171], off
	v_lshl_add_u64 v[170:171], s[6:7], 0, v[146:147]
	s_add_i32 m0, s8, 0x2000
	s_nop 0
	global_load_lds_dwordx4 v[170:171], off
	v_lshl_add_u64 v[170:171], v[212:213], 0, s[74:75]
	s_mov_b32 m0, s43
	s_nop 0
	global_load_lds_dwordx4 v[170:171], off
	v_lshl_add_u64 v[170:171], v[214:215], 0, s[74:75]
	s_mov_b32 m0, s44
	s_nop 0
	global_load_lds_dwordx4 v[170:171], off
	s_waitcnt vmcnt(8)
	s_waitcnt lgkmcnt(0)
	s_barrier
	s_setprio 1
	s_waitcnt lgkmcnt(0)
	v_mfma_f32_16x16x32_bf16 v[78:81], v[58:61], v[178:181], v[78:81]
	v_mfma_f32_16x16x32_bf16 v[74:77], v[66:69], v[178:181], v[74:77]
	v_mfma_f32_16x16x32_bf16 v[54:57], v[58:61], v[186:189], v[54:57]
	v_mfma_f32_16x16x32_bf16 v[50:53], v[66:69], v[186:189], v[50:53]
	v_mfma_f32_16x16x32_bf16 v[30:33], v[58:61], v[194:197], v[30:33]
	v_mfma_f32_16x16x32_bf16 v[26:29], v[66:69], v[194:197], v[26:29]
	v_mfma_f32_16x16x32_bf16 v[14:17], v[58:61], v[202:205], v[14:17]
	v_mfma_f32_16x16x32_bf16 v[10:13], v[66:69], v[202:205], v[10:13]
	v_mfma_f32_16x16x32_bf16 v[78:81], v[62:65], v[182:185], v[78:81]
	v_mfma_f32_16x16x32_bf16 v[74:77], v[70:73], v[182:185], v[74:77]
	v_mfma_f32_16x16x32_bf16 v[54:57], v[62:65], v[190:193], v[54:57]
	v_mfma_f32_16x16x32_bf16 v[50:53], v[70:73], v[190:193], v[50:53]
	v_mfma_f32_16x16x32_bf16 v[30:33], v[62:65], v[198:201], v[30:33]
	v_mfma_f32_16x16x32_bf16 v[26:29], v[70:73], v[198:201], v[26:29]
	v_mfma_f32_16x16x32_bf16 v[14:17], v[62:65], v[206:209], v[14:17]
	v_mfma_f32_16x16x32_bf16 v[10:13], v[70:73], v[206:209], v[10:13]
	s_setprio 0
	s_setprio 1
	v_mfma_f32_16x16x32_bf16 v[42:45], v[158:161], v[178:181], v[42:45]
	v_mfma_f32_16x16x32_bf16 v[70:73], v[162:165], v[182:185], v[42:45]
	v_mfma_f32_16x16x32_bf16 v[42:45], v[166:169], v[178:181], v[46:49]
	v_mfma_f32_16x16x32_bf16 v[38:41], v[158:161], v[186:189], v[38:41]
	v_mfma_f32_16x16x32_bf16 v[34:37], v[166:169], v[186:189], v[34:37]
	v_mfma_f32_16x16x32_bf16 v[22:25], v[158:161], v[194:197], v[22:25]
	v_mfma_f32_16x16x32_bf16 v[18:21], v[166:169], v[194:197], v[18:21]
	v_mfma_f32_16x16x32_bf16 v[6:9], v[158:161], v[202:205], v[6:9]
	v_mfma_f32_16x16x32_bf16 v[2:5], v[166:169], v[202:205], v[2:5]
	v_mfma_f32_16x16x32_bf16 v[66:69], v[174:177], v[182:185], v[42:45]
	v_mfma_f32_16x16x32_bf16 v[38:41], v[162:165], v[190:193], v[38:41]
	v_mfma_f32_16x16x32_bf16 v[34:37], v[174:177], v[190:193], v[34:37]
	v_mfma_f32_16x16x32_bf16 v[22:25], v[162:165], v[198:201], v[22:25]
	v_mfma_f32_16x16x32_bf16 v[18:21], v[174:177], v[198:201], v[18:21]
	v_mfma_f32_16x16x32_bf16 v[6:9], v[162:165], v[206:209], v[6:9]
	v_mfma_f32_16x16x32_bf16 v[2:5], v[174:177], v[206:209], v[2:5]
	s_setprio 0
	s_barrier
	s_add_i32 s46, s46, 2
	s_add_u32 s4, s4, 0x100
	s_addc_u32 s5, s5, 0
	s_add_u32 s30, s30, 0x100
	s_addc_u32 s31, s31, 0
	s_cmp_gt_u32 s46, 13
	s_cbranch_scc0 .LBB0_259
	s_and_b64 vcc, exec, s[12:13]
	s_cbranch_vccz .LBB0_262
	s_barrier

; #define PG8_STAGE(bufoff, gbase, voff) do { _Pragma("unroll") for (int _i = 0; _i < 2; ++_i) \
;         __builtin_amdgcn_global_load_lds((const unsigned*)((const char*)(gbase) + (voff)[_i]), (LAS unsigned*)(lds + (bufoff) + ldsw + _i * 8192), 16, 0, 0); } while (0)
; #define PG8_LDA(dst, b, h) do { _Pragma("unroll") for (int m = 0; m < 4; ++m) _Pragma("unroll") for (int k = 0; k < 2; ++k) dst[m][k] = *(const LAS bf16x8*)(lds + PG8_SA(b, h) + aoff + m * 2048 + k * 1024); } while (0)
; #define PG8_LDB(dst, b, h) do { _Pragma("unroll") for (int n = 0; n < 2; ++n) _Pragma("unroll") for (int k = 0; k < 2; ++k) dst[n][k] = *(const LAS bf16x8*)(lds + PG8_SB(b, h) + boff + n * 2048 + k * 1024); } while (0)
; #define PG8_MMA(ai, bj, At, Bt) do { __builtin_amdgcn_s_setprio(1); _Pragma("unroll") for (int m = 0; m < 4; ++m) _Pragma("unroll") for (int n = 0; n < 2; ++n) _Pragma("unroll") for (int k = 0; k < 2; ++k) \
;         acc[ai][bj][m][n] = __builtin_amdgcn_mfma_f32_16x16x32_bf16(Bt[n][k], At[m][k], acc[ai][bj][m][n], 0, 0, 0); __builtin_amdgcn_s_setprio(0); } while (0)
; #define PG8_WAIT_V(n) asm volatile("s_waitcnt vmcnt(" #n ")" ::: "memory")
; #define PG8_WAIT_L(n) asm volatile("s_waitcnt lgkmcnt(" #n ")" ::: "memory")
; #define PG8_BAR __builtin_amdgcn_s_barrier()
; template <class Epi, class Sched, bool ALIGN_EPI>
; __device__ __forceinline__ void gemm_phase(LAS unsigned char* lds, const Gemm g, const Sched& S, const Epi& E, int wave_s) {
;     ...
;         for (int t = 0; t < nt; t += 2) {
;             const bool last = (t == nt - 2);
;             const char* a1 = cA + (size_t)(t + 1) * kstep;
;             const char* a2 = last ? nA : cA + (size_t)(t + 2) * kstep; const char* b2 = last ? nB : cB + (size_t)(t + 2) * kstep;
;             const char* a3 = a2 + kstep; const char* b3 = b2 + kstep;
;             PG8_LDB(B0, 0, 0); PG8_LDB(B1, 0, 1); PG8_SCHED; PG8_LDA(At, 0, 0); PG8_STAGE(PG8_SA(1, 1), a1 + hstepA, voffA);
;             PG8_WAIT_V(8); PG8_WAIT_L(0); PG8_BAR; PG8_MMA(0, 0, At, B0); PG8_MMA(0, 1, At, B1); PG8_BAR; PG8_SCHED;
;     ...
; #pragma unroll
;         for (int a = 0; a < 2; ++a)
; #pragma unroll
;             for (int b = 0; b < 2; ++b)
; #pragma unroll
;                 for (int m = 0; m < 4; ++m)
; #pragma unroll
;                     for (int n = 0; n < 2; ++n) acc[a][b][m][n] = (f32x4){0.f, 0.f, 0.f, 0.f};
.LBB0_405:
	s_add_u32 s6, s4, 0xfffc0080
	s_addc_u32 s7, s5, -1
	s_add_i32 s35, 0, 0x10000
	s_cmp_eq_u32 s34, 12
	s_cselect_b32 s9, s21, s7
	s_cselect_b32 s8, s27, s6
	v_add_u32_e32 v2, s35, v1
	s_cselect_b32 s7, s19, s31
	s_cselect_b32 s6, s28, s29
	s_add_i32 s50, 0, 0x14000
	ds_read_b128 v[34:37], v2
	ds_read_b128 v[38:41], v2 offset:1024
	ds_read_b128 v[50:53], v2 offset:2048
	ds_read_b128 v[54:57], v2 offset:3072
	v_add_u32_e32 v2, s50, v1
	ds_read_b128 v[150:153], v2
	ds_read_b128 v[154:157], v2 offset:1024
	ds_read_b128 v[158:161], v2 offset:2048
	ds_read_b128 v[162:165], v2 offset:3072
	v_lshl_add_u64 v[2:3], s[4:5], 0, v[174:175]
	s_add_i32 m0, s39, 0xc000
	ds_read_b128 v[178:181], v188
	ds_read_b128 v[182:185], v188 offset:1024
	ds_read_b128 v[190:193], v188 offset:2048
	ds_read_b128 v[194:197], v188 offset:3072
	ds_read_b128 v[198:201], v188 offset:4096
	ds_read_b128 v[202:205], v188 offset:5120
	ds_read_b128 v[206:209], v188 offset:6144
	ds_read_b128 v[210:213], v188 offset:7168
	global_load_lds_dwordx4 v[2:3], off
	v_lshl_add_u64 v[2:3], s[4:5], 0, v[176:177]
	s_add_i32 m0, s39, 0xe000
	s_nop 0
	global_load_lds_dwordx4 v[2:3], off
	s_cmp_lg_u32 s34, -2
	s_cbranch_scc1 .Lzacc_405_skip
	v_mov_b32_e32 v11, 0
	v_mov_b32_e32 v12, 0
	v_mov_b32_e32 v13, 0
	v_mov_b32_e32 v14, 0
	v_mov_b32_e32 v15, 0
	v_mov_b32_e32 v16, 0
	v_mov_b32_e32 v17, 0
	v_mov_b32_e32 v26, 0
	v_mov_b32_e32 v27, 0
	v_mov_b32_e32 v28, 0
	v_mov_b32_e32 v29, 0
	v_mov_b32_e32 v30, 0
	v_mov_b32_e32 v31, 0
	v_mov_b32_e32 v32, 0
	v_mov_b32_e32 v33, 0
	v_mov_b32_e32 v58, 0
	v_mov_b32_e32 v59, 0
	v_mov_b32_e32 v60, 0
	v_mov_b32_e32 v61, 0
	v_mov_b32_e32 v62, 0
	v_mov_b32_e32 v63, 0
	v_mov_b32_e32 v64, 0
	v_mov_b32_e32 v65, 0
	v_mov_b32_e32 v74, 0
	v_mov_b32_e32 v75, 0
	v_mov_b32_e32 v76, 0
	v_mov_b32_e32 v77, 0
	v_mov_b32_e32 v78, 0
	v_mov_b32_e32 v79, 0
	v_mov_b32_e32 v80, 0
	v_mov_b32_e32 v81, 0
	v_mov_b32_e32 v18, 0
	v_mov_b32_e32 v19, 0
	v_mov_b32_e32 v20, 0
	v_mov_b32_e32 v21, 0
	v_mov_b32_e32 v22, 0
	v_mov_b32_e32 v23, 0
	v_mov_b32_e32 v24, 0
	v_mov_b32_e32 v25, 0
	v_mov_b32_e32 v42, 0
	v_mov_b32_e32 v43, 0
	v_mov_b32_e32 v44, 0
	v_mov_b32_e32 v45, 0
	v_mov_b32_e32 v46, 0
	v_mov_b32_e32 v47, 0
	v_mov_b32_e32 v48, 0
	v_mov_b32_e32 v49, 0
	v_mov_b32_e32 v66, 0
	v_mov_b32_e32 v67, 0
	v_mov_b32_e32 v68, 0
	v_mov_b32_e32 v69, 0
	v_mov_b32_e32 v70, 0
	v_mov_b32_e32 v71, 0
	v_mov_b32_e32 v72, 0
	v_mov_b32_e32 v73, 0
	v_mov_b32_e32 v82, 0
	v_mov_b32_e32 v83, 0
	v_mov_b32_e32 v84, 0
	v_mov_b32_e32 v85, 0
	v_mov_b32_e32 v86, 0
	v_mov_b32_e32 v87, 0
	v_mov_b32_e32 v88, 0
	v_mov_b32_e32 v89, 0
	v_mov_b32_e32 v90, 0
	v_mov_b32_e32 v91, 0
	v_mov_b32_e32 v92, 0
	v_mov_b32_e32 v93, 0
	v_mov_b32_e32 v94, 0
	v_mov_b32_e32 v95, 0
	v_mov_b32_e32 v96, 0
	v_mov_b32_e32 v97, 0
	v_mov_b32_e32 v106, 0
	v_mov_b32_e32 v107, 0
	v_mov_b32_e32 v108, 0
	v_mov_b32_e32 v109, 0
	v_mov_b32_e32 v110, 0
	v_mov_b32_e32 v111, 0
	v_mov_b32_e32 v112, 0
	v_mov_b32_e32 v113, 0
	v_mov_b32_e32 v122, 0
	v_mov_b32_e32 v123, 0
	v_mov_b32_e32 v124, 0
	v_mov_b32_e32 v125, 0
	v_mov_b32_e32 v126, 0
	v_mov_b32_e32 v127, 0
	v_mov_b32_e32 v128, 0
	v_mov_b32_e32 v129, 0
	v_mov_b32_e32 v138, 0
	v_mov_b32_e32 v139, 0
	v_mov_b32_e32 v140, 0
	v_mov_b32_e32 v141, 0
	v_mov_b32_e32 v142, 0
	v_mov_b32_e32 v143, 0
	v_mov_b32_e32 v144, 0
	v_mov_b32_e32 v145, 0
	v_mov_b32_e32 v98, 0
	v_mov_b32_e32 v99, 0
	v_mov_b32_e32 v100, 0
	v_mov_b32_e32 v101, 0
	v_mov_b32_e32 v102, 0
	v_mov_b32_e32 v103, 0
	v_mov_b32_e32 v104, 0
	v_mov_b32_e32 v105, 0
	v_mov_b32_e32 v114, 0
	v_mov_b32_e32 v115, 0
	v_mov_b32_e32 v116, 0
	v_mov_b32_e32 v117, 0
	v_mov_b32_e32 v118, 0
	v_mov_b32_e32 v119, 0
	v_mov_b32_e32 v120, 0
	v_mov_b32_e32 v121, 0
	v_mov_b32_e32 v130, 0
	v_mov_b32_e32 v131, 0
	v_mov_b32_e32 v132, 0
	v_mov_b32_e32 v133, 0
	v_mov_b32_e32 v134, 0
	v_mov_b32_e32 v135, 0
	v_mov_b32_e32 v136, 0
	v_mov_b32_e32 v137, 0
	v_mov_b32_e32 v4, 0
	v_mov_b32_e32 v5, 0
	v_mov_b32_e32 v6, 0
	v_mov_b32_e32 v7, 0
	v_mov_b32_e32 v146, 0
	v_mov_b32_e32 v147, 0
	v_mov_b32_e32 v148, 0
	v_mov_b32_e32 v149, 0
.Lzacc_405_skip:
	s_waitcnt vmcnt(8)
	s_waitcnt lgkmcnt(0)
	s_barrier
	s_setprio 1
	s_waitcnt lgkmcnt(0)
	v_mfma_f32_16x16x32_bf16 v[2:5], v[50:53], v[178:181], v[4:7]
	v_mfma_f32_16x16x32_bf16 v[6:9], v[34:37], v[190:193], v[134:137]
	v_mfma_f32_16x16x32_bf16 v[134:137], v[38:41], v[194:197], v[6:9]
	v_mfma_f32_16x16x32_bf16 v[6:9], v[50:53], v[190:193], v[130:133]
	v_mfma_f32_16x16x32_bf16 v[130:133], v[54:57], v[194:197], v[6:9]
	v_mfma_f32_16x16x32_bf16 v[6:9], v[34:37], v[198:201], v[118:121]
	v_mfma_f32_16x16x32_bf16 v[118:121], v[38:41], v[202:205], v[6:9]
	v_mfma_f32_16x16x32_bf16 v[6:9], v[50:53], v[198:201], v[114:117]
	v_mfma_f32_16x16x32_bf16 v[114:117], v[54:57], v[202:205], v[6:9]
	v_mfma_f32_16x16x32_bf16 v[6:9], v[34:37], v[206:209], v[102:105]
	v_mfma_f32_16x16x32_bf16 v[146:149], v[34:37], v[178:181], v[146:149]
	v_mfma_f32_16x16x32_bf16 v[102:105], v[38:41], v[210:213], v[6:9]
	v_mfma_f32_16x16x32_bf16 v[6:9], v[50:53], v[206:209], v[98:101]
	v_mfma_f32_16x16x32_bf16 v[146:149], v[38:41], v[182:185], v[146:149]
	v_mfma_f32_16x16x32_bf16 v[2:5], v[54:57], v[182:185], v[2:5]
	v_mfma_f32_16x16x32_bf16 v[98:101], v[54:57], v[210:213], v[6:9]
	s_setprio 0
	s_setprio 1
	v_mfma_f32_16x16x32_bf16 v[6:9], v[150:153], v[178:181], v[142:145]
	v_mfma_f32_16x16x32_bf16 v[142:145], v[154:157], v[182:185], v[6:9]
	v_mfma_f32_16x16x32_bf16 v[6:9], v[158:161], v[178:181], v[138:141]
	v_mfma_f32_16x16x32_bf16 v[138:141], v[162:165], v[182:185], v[6:9]
	v_mfma_f32_16x16x32_bf16 v[6:9], v[150:153], v[190:193], v[126:129]
	v_mfma_f32_16x16x32_bf16 v[126:129], v[154:157], v[194:197], v[6:9]
	v_mfma_f32_16x16x32_bf16 v[6:9], v[158:161], v[190:193], v[122:125]
	v_mfma_f32_16x16x32_bf16 v[122:125], v[162:165], v[194:197], v[6:9]
	v_mfma_f32_16x16x32_bf16 v[6:9], v[150:153], v[198:201], v[110:113]
	v_mfma_f32_16x16x32_bf16 v[110:113], v[154:157], v[202:205], v[6:9]
	v_mfma_f32_16x16x32_bf16 v[6:9], v[158:161], v[198:201], v[106:109]
	v_mfma_f32_16x16x32_bf16 v[106:109], v[162:165], v[202:205], v[6:9]
	v_mfma_f32_16x16x32_bf16 v[6:9], v[150:153], v[206:209], v[94:97]
	v_mfma_f32_16x16x32_bf16 v[94:97], v[154:157], v[210:213], v[6:9]
	v_mfma_f32_16x16x32_bf16 v[6:9], v[158:161], v[206:209], v[90:93]
	v_mfma_f32_16x16x32_bf16 v[90:93], v[162:165], v[210:213], v[6:9]
	s_setprio 0
	s_barrier
; #define PG8_STAGE(bufoff, gbase, voff) do { _Pragma("unroll") for (int _i = 0; _i < 2; ++_i) \
;         __builtin_amdgcn_global_load_lds((const unsigned*)((const char*)(gbase) + (voff)[_i]), (LAS unsigned*)(lds + (bufoff) + ldsw + _i * 8192), 16, 0, 0); } while (0)
; #define PG8_LDA(dst, b, h) do { _Pragma("unroll") for (int m = 0; m < 4; ++m) _Pragma("unroll") for (int k = 0; k < 2; ++k) dst[m][k] = *(const LAS bf16x8*)(lds + PG8_SA(b, h) + aoff + m * 2048 + k * 1024); } while (0)
; #define PG8_LDB(dst, b, h) do { _Pragma("unroll") for (int n = 0; n < 2; ++n) _Pragma("unroll") for (int k = 0; k < 2; ++k) dst[n][k] = *(const LAS bf16x8*)(lds + PG8_SB(b, h) + boff + n * 2048 + k * 1024); } while (0)
; #define PG8_MMA(ai, bj, At, Bt) do { __builtin_amdgcn_s_setprio(1); _Pragma("unroll") for (int m = 0; m < 4; ++m) _Pragma("unroll") for (int n = 0; n < 2; ++n) _Pragma("unroll") for (int k = 0; k < 2; ++k) \
;         acc[ai][bj][m][n] = __builtin_amdgcn_mfma_f32_16x16x32_bf16(Bt[n][k], At[m][k], acc[ai][bj][m][n], 0, 0, 0); __builtin_amdgcn_s_setprio(0); } while (0)
; #define PG8_WAIT_V(n) asm volatile("s_waitcnt vmcnt(" #n ")" ::: "memory")
; #define PG8_WAIT_L(n) asm volatile("s_waitcnt lgkmcnt(" #n ")" ::: "memory")
; #define PG8_BAR __builtin_amdgcn_s_barrier()
; #define PG8_SCHED __builtin_amdgcn_sched_barrier(0)
; template <class Epi, class Sched, bool ALIGN_EPI>
; __device__ __forceinline__ void gemm_phase(LAS unsigned char* lds, const Gemm g, const Sched& S, const Epi& E, int wave_s) {
;     ...
;             PG8_LDA(At, 0, 1); PG8_STAGE(PG8_SB(0, 0), b2, voffB); PG8_STAGE(PG8_SB(0, 1), b2 + hstepB, voffB); PG8_STAGE(PG8_SA(0, 0), a2, voffA);
;             PG8_WAIT_V(8); PG8_WAIT_L(0); PG8_BAR; PG8_MMA(1, 0, At, B0); PG8_MMA(1, 1, At, B1); PG8_BAR; PG8_SCHED;
;             PG8_LDB(B0, 1, 0); PG8_LDB(B1, 1, 1); PG8_SCHED; PG8_LDA(At, 1, 0); PG8_STAGE(PG8_SA(0, 1), a2 + hstepA, voffA);
;             PG8_WAIT_V(8); PG8_WAIT_L(0); PG8_BAR; PG8_MMA(0, 0, At, B0); PG8_MMA(0, 1, At, B1); PG8_BAR; PG8_SCHED;
	s_add_i32 s35, s35, s38
	v_lshl_add_u64 v[186:187], s[6:7], 0, v[170:171]
	s_mov_b32 m0, s35
	s_nop 1
	ds_read_b128 v[6:9], v188 offset:16384
	ds_read_b128 v[178:181], v188 offset:17408
	ds_read_b128 v[182:185], v188 offset:18432
	ds_read_b128 v[190:193], v188 offset:19456
	ds_read_b128 v[194:197], v188 offset:20480
	ds_read_b128 v[198:201], v188 offset:21504
	ds_read_b128 v[202:205], v188 offset:22528
	ds_read_b128 v[206:209], v188 offset:23552
	global_load_lds_dwordx4 v[186:187], off
	s_add_i32 m0, s35, 0x2000
	s_add_u32 s36, s6, 0x40000
	v_lshl_add_u64 v[214:215], s[6:7], 0, v[166:167]
	s_addc_u32 s37, s7, 0
	s_add_i32 s35, s50, s38
	global_load_lds_dwordx4 v[214:215], off
	v_lshl_add_u64 v[210:211], s[36:37], 0, v[170:171]
	s_mov_b32 m0, s35
	v_lshl_add_u64 v[216:217], s[8:9], 0, v[172:173]
	global_load_lds_dwordx4 v[210:211], off
	v_lshl_add_u64 v[210:211], s[36:37], 0, v[166:167]
	s_add_i32 m0, s35, 0x2000
	v_lshl_add_u64 v[218:219], s[8:9], 0, v[168:169]
	global_load_lds_dwordx4 v[210:211], off
	s_mov_b32 m0, s39
	s_nop 0
	global_load_lds_dwordx4 v[216:217], off
	s_mov_b32 m0, s42
	s_nop 0
	global_load_lds_dwordx4 v[218:219], off
	s_waitcnt vmcnt(8)
	s_waitcnt lgkmcnt(0)
	s_barrier
	s_setprio 1
	s_waitcnt lgkmcnt(0)
	v_mfma_f32_16x16x32_bf16 v[86:89], v[34:37], v[6:9], v[86:89]
	v_mfma_f32_16x16x32_bf16 v[82:85], v[50:53], v[6:9], v[82:85]
	v_mfma_f32_16x16x32_bf16 v[70:73], v[34:37], v[182:185], v[70:73]
	v_mfma_f32_16x16x32_bf16 v[66:69], v[50:53], v[182:185], v[66:69]
	v_mfma_f32_16x16x32_bf16 v[46:49], v[34:37], v[194:197], v[46:49]
	v_mfma_f32_16x16x32_bf16 v[42:45], v[50:53], v[194:197], v[42:45]
	v_mfma_f32_16x16x32_bf16 v[22:25], v[34:37], v[202:205], v[22:25]
	v_mfma_f32_16x16x32_bf16 v[18:21], v[50:53], v[202:205], v[18:21]
	v_mfma_f32_16x16x32_bf16 v[86:89], v[38:41], v[178:181], v[86:89]
	v_mfma_f32_16x16x32_bf16 v[82:85], v[54:57], v[178:181], v[82:85]
	v_mfma_f32_16x16x32_bf16 v[70:73], v[38:41], v[190:193], v[70:73]
	v_mfma_f32_16x16x32_bf16 v[66:69], v[54:57], v[190:193], v[66:69]
	v_mfma_f32_16x16x32_bf16 v[46:49], v[38:41], v[198:201], v[46:49]
	v_mfma_f32_16x16x32_bf16 v[42:45], v[54:57], v[198:201], v[42:45]
	v_mfma_f32_16x16x32_bf16 v[22:25], v[38:41], v[206:209], v[22:25]
	v_mfma_f32_16x16x32_bf16 v[18:21], v[54:57], v[206:209], v[18:21]
	s_setprio 0
	s_setprio 1
	v_mfma_f32_16x16x32_bf16 v[34:37], v[150:153], v[6:9], v[78:81]
	v_mfma_f32_16x16x32_bf16 v[6:9], v[158:161], v[6:9], v[74:77]
	v_mfma_f32_16x16x32_bf16 v[38:41], v[162:165], v[178:181], v[6:9]
	v_mfma_f32_16x16x32_bf16 v[6:9], v[150:153], v[182:185], v[62:65]
	v_mfma_f32_16x16x32_bf16 v[50:53], v[154:157], v[190:193], v[6:9]
	v_mfma_f32_16x16x32_bf16 v[6:9], v[158:161], v[182:185], v[58:61]
	v_mfma_f32_16x16x32_bf16 v[54:57], v[162:165], v[190:193], v[6:9]
	v_mfma_f32_16x16x32_bf16 v[6:9], v[150:153], v[194:197], v[30:33]
	v_mfma_f32_16x16x32_bf16 v[30:33], v[154:157], v[198:201], v[6:9]
	v_mfma_f32_16x16x32_bf16 v[6:9], v[158:161], v[194:197], v[26:29]
	v_mfma_f32_16x16x32_bf16 v[26:29], v[162:165], v[198:201], v[6:9]
	v_mfma_f32_16x16x32_bf16 v[6:9], v[150:153], v[202:205], v[14:17]
	v_mfma_f32_16x16x32_bf16 v[14:17], v[154:157], v[206:209], v[6:9]
	v_mfma_f32_16x16x32_bf16 v[6:9], v[158:161], v[202:205], v[10:13]
	v_mfma_f32_16x16x32_bf16 v[8:11], v[162:165], v[206:209], v[6:9]
	v_mfma_f32_16x16x32_bf16 v[34:37], v[154:157], v[178:181], v[34:37]
	s_setprio 0
	s_barrier
	s_add_i32 s35, 0, 0x18000
	s_nop 2
	v_add_u32_e32 v6, s35, v1
	s_add_i32 s36, 0, 0x1c000
	ds_read_b128 v[58:61], v6
	ds_read_b128 v[62:65], v6 offset:1024
	ds_read_b128 v[74:77], v6 offset:2048
	ds_read_b128 v[78:81], v6 offset:3072
	v_add_u32_e32 v6, s36, v1
	ds_read_b128 v[150:153], v6
	ds_read_b128 v[154:157], v6 offset:1024
	ds_read_b128 v[158:161], v6 offset:2048
	ds_read_b128 v[162:165], v6 offset:3072
	s_add_u32 s8, s8, 0x40000
	s_addc_u32 s9, s9, 0
	s_mov_b32 m0, s43
	v_lshl_add_u64 v[6:7], s[8:9], 0, v[172:173]
	ds_read_b128 v[178:181], v188 offset:32768
	ds_read_b128 v[182:185], v188 offset:33792
	ds_read_b128 v[190:193], v188 offset:34816
	ds_read_b128 v[194:197], v188 offset:35840
	ds_read_b128 v[198:201], v188 offset:36864
	ds_read_b128 v[202:205], v188 offset:37888
	ds_read_b128 v[206:209], v188 offset:38912
	ds_read_b128 v[210:213], v188 offset:39936
	global_load_lds_dwordx4 v[6:7], off
	v_lshl_add_u64 v[6:7], s[8:9], 0, v[168:169]
	s_mov_b32 m0, s44
	s_nop 0
	global_load_lds_dwordx4 v[6:7], off
	s_waitcnt vmcnt(8)
	s_waitcnt lgkmcnt(0)
	s_barrier
; #define PG8_STAGE(bufoff, gbase, voff) do { _Pragma("unroll") for (int _i = 0; _i < 2; ++_i) \
;         __builtin_amdgcn_global_load_lds((const unsigned*)((const char*)(gbase) + (voff)[_i]), (LAS unsigned*)(lds + (bufoff) + ldsw + _i * 8192), 16, 0, 0); } while (0)
; #define PG8_LDA(dst, b, h) do { _Pragma("unroll") for (int m = 0; m < 4; ++m) _Pragma("unroll") for (int k = 0; k < 2; ++k) dst[m][k] = *(const LAS bf16x8*)(lds + PG8_SA(b, h) + aoff + m * 2048 + k * 1024); } while (0)
; #define PG8_MMA(ai, bj, At, Bt) do { __builtin_amdgcn_s_setprio(1); _Pragma("unroll") for (int m = 0; m < 4; ++m) _Pragma("unroll") for (int n = 0; n < 2; ++n) _Pragma("unroll") for (int k = 0; k < 2; ++k) \
;         acc[ai][bj][m][n] = __builtin_amdgcn_mfma_f32_16x16x32_bf16(Bt[n][k], At[m][k], acc[ai][bj][m][n], 0, 0, 0); __builtin_amdgcn_s_setprio(0); } while (0)
; #define PG8_WAIT_V(n) asm volatile("s_waitcnt vmcnt(" #n ")" ::: "memory")
; #define PG8_WAIT_L(n) asm volatile("s_waitcnt lgkmcnt(" #n ")" ::: "memory")
; #define PG8_BAR __builtin_amdgcn_s_barrier()
; #define PG8_SCHED __builtin_amdgcn_sched_barrier(0)
; template <class Epi, class Sched, bool ALIGN_EPI>
; __device__ __forceinline__ void gemm_phase(LAS unsigned char* lds, const Gemm g, const Sched& S, const Epi& E, int wave_s) {
;     ...
;             PG8_WAIT_V(8); PG8_WAIT_L(0); PG8_BAR; PG8_MMA(0, 0, At, B0); PG8_MMA(0, 1, At, B1); PG8_BAR; PG8_SCHED;
;             PG8_LDA(At, 1, 1); PG8_STAGE(PG8_SB(1, 0), b3, voffB); PG8_STAGE(PG8_SB(1, 1), b3 + hstepB, voffB); PG8_STAGE(PG8_SA(1, 0), a3, voffA);
;             PG8_WAIT_V(8); PG8_WAIT_L(0); PG8_BAR; PG8_MMA(1, 0, At, B0); PG8_MMA(1, 1, At, B1); PG8_BAR; PG8_SCHED;
;         }
;         if constexpr (ALIGN_EPI) { if (wr == 0) PG8_BAR; }
;         E(acc, cur, wr, wc, fr, fq);
;         if (!has_next) break;
	s_setprio 1
	s_waitcnt lgkmcnt(0)
	v_mfma_f32_16x16x32_bf16 v[146:149], v[58:61], v[178:181], v[146:149]
	v_mfma_f32_16x16x32_bf16 v[2:5], v[74:77], v[178:181], v[2:5]
	v_mfma_f32_16x16x32_bf16 v[134:137], v[58:61], v[190:193], v[134:137]
	v_mfma_f32_16x16x32_bf16 v[130:133], v[74:77], v[190:193], v[130:133]
	v_mfma_f32_16x16x32_bf16 v[118:121], v[58:61], v[198:201], v[118:121]
	v_mfma_f32_16x16x32_bf16 v[114:117], v[74:77], v[198:201], v[114:117]
	v_mfma_f32_16x16x32_bf16 v[102:105], v[58:61], v[206:209], v[102:105]
	v_mfma_f32_16x16x32_bf16 v[98:101], v[74:77], v[206:209], v[98:101]
	v_mfma_f32_16x16x32_bf16 v[146:149], v[62:65], v[182:185], v[146:149]
	v_mfma_f32_16x16x32_bf16 v[4:7], v[78:81], v[182:185], v[2:5]
	v_mfma_f32_16x16x32_bf16 v[134:137], v[62:65], v[194:197], v[134:137]
	v_mfma_f32_16x16x32_bf16 v[130:133], v[78:81], v[194:197], v[130:133]
	v_mfma_f32_16x16x32_bf16 v[118:121], v[62:65], v[202:205], v[118:121]
	v_mfma_f32_16x16x32_bf16 v[114:117], v[78:81], v[202:205], v[114:117]
	v_mfma_f32_16x16x32_bf16 v[102:105], v[62:65], v[210:213], v[102:105]
	v_mfma_f32_16x16x32_bf16 v[98:101], v[78:81], v[210:213], v[98:101]
	s_setprio 0
	s_setprio 1
	v_mfma_f32_16x16x32_bf16 v[142:145], v[150:153], v[178:181], v[142:145]
	v_mfma_f32_16x16x32_bf16 v[138:141], v[158:161], v[178:181], v[138:141]
	v_mfma_f32_16x16x32_bf16 v[126:129], v[150:153], v[190:193], v[126:129]
	v_mfma_f32_16x16x32_bf16 v[122:125], v[158:161], v[190:193], v[122:125]
	v_mfma_f32_16x16x32_bf16 v[110:113], v[150:153], v[198:201], v[110:113]
	v_mfma_f32_16x16x32_bf16 v[106:109], v[158:161], v[198:201], v[106:109]
	v_mfma_f32_16x16x32_bf16 v[94:97], v[150:153], v[206:209], v[94:97]
	v_mfma_f32_16x16x32_bf16 v[90:93], v[158:161], v[206:209], v[90:93]
	v_mfma_f32_16x16x32_bf16 v[142:145], v[154:157], v[182:185], v[142:145]
	v_mfma_f32_16x16x32_bf16 v[138:141], v[162:165], v[182:185], v[138:141]
	v_mfma_f32_16x16x32_bf16 v[126:129], v[154:157], v[194:197], v[126:129]
	v_mfma_f32_16x16x32_bf16 v[122:125], v[162:165], v[194:197], v[122:125]
	v_mfma_f32_16x16x32_bf16 v[110:113], v[154:157], v[202:205], v[110:113]
	v_mfma_f32_16x16x32_bf16 v[106:109], v[162:165], v[202:205], v[106:109]
	v_mfma_f32_16x16x32_bf16 v[94:97], v[154:157], v[210:213], v[94:97]
	v_mfma_f32_16x16x32_bf16 v[90:93], v[162:165], v[210:213], v[90:93]
	s_setprio 0
	s_barrier
	s_add_i32 s8, s35, s38
	v_lshl_add_u64 v[2:3], v[186:187], 0, s[74:75]
	s_mov_b32 m0, s8
	ds_read_b128 v[178:181], v188 offset:49152
	ds_read_b128 v[182:185], v188 offset:50176
	ds_read_b128 v[190:193], v188 offset:51200
	ds_read_b128 v[194:197], v188 offset:52224
	ds_read_b128 v[198:201], v188 offset:53248
	ds_read_b128 v[202:205], v188 offset:54272
	ds_read_b128 v[206:209], v188 offset:55296
	ds_read_b128 v[210:213], v188 offset:56320
	global_load_lds_dwordx4 v[2:3], off
	s_add_i32 m0, s8, 0x2000
	s_add_u32 s6, s6, 0x40080
	v_lshl_add_u64 v[2:3], v[214:215], 0, s[74:75]
	s_addc_u32 s7, s7, 0
	s_add_i32 s8, s36, s38
	global_load_lds_dwordx4 v[2:3], off
	v_lshl_add_u64 v[2:3], s[6:7], 0, v[170:171]
	s_mov_b32 m0, s8
	s_nop 0
	global_load_lds_dwordx4 v[2:3], off
	v_lshl_add_u64 v[2:3], s[6:7], 0, v[166:167]
	s_add_i32 m0, s8, 0x2000
	s_nop 0
	global_load_lds_dwordx4 v[2:3], off
	v_lshl_add_u64 v[2:3], v[216:217], 0, s[74:75]
	s_mov_b32 m0, s47
	s_nop 0
	global_load_lds_dwordx4 v[2:3], off
	v_lshl_add_u64 v[2:3], v[218:219], 0, s[74:75]
	s_mov_b32 m0, s48
	s_nop 0
	global_load_lds_dwordx4 v[2:3], off
	s_waitcnt vmcnt(8)
	s_waitcnt lgkmcnt(0)
	s_barrier
	s_setprio 1
	s_waitcnt lgkmcnt(0)
	v_mfma_f32_16x16x32_bf16 v[86:89], v[58:61], v[178:181], v[86:89]
	v_mfma_f32_16x16x32_bf16 v[82:85], v[74:77], v[178:181], v[82:85]
	v_mfma_f32_16x16x32_bf16 v[70:73], v[58:61], v[190:193], v[70:73]
	v_mfma_f32_16x16x32_bf16 v[66:69], v[74:77], v[190:193], v[66:69]
	v_mfma_f32_16x16x32_bf16 v[46:49], v[58:61], v[198:201], v[46:49]
	v_mfma_f32_16x16x32_bf16 v[42:45], v[74:77], v[198:201], v[42:45]
	v_mfma_f32_16x16x32_bf16 v[22:25], v[58:61], v[206:209], v[22:25]
	v_mfma_f32_16x16x32_bf16 v[18:21], v[74:77], v[206:209], v[18:21]
	v_mfma_f32_16x16x32_bf16 v[86:89], v[62:65], v[182:185], v[86:89]
	v_mfma_f32_16x16x32_bf16 v[82:85], v[78:81], v[182:185], v[82:85]
	v_mfma_f32_16x16x32_bf16 v[70:73], v[62:65], v[194:197], v[70:73]
	v_mfma_f32_16x16x32_bf16 v[66:69], v[78:81], v[194:197], v[66:69]
	v_mfma_f32_16x16x32_bf16 v[46:49], v[62:65], v[202:205], v[46:49]
	v_mfma_f32_16x16x32_bf16 v[42:45], v[78:81], v[202:205], v[42:45]
	v_mfma_f32_16x16x32_bf16 v[22:25], v[62:65], v[210:213], v[22:25]
	v_mfma_f32_16x16x32_bf16 v[18:21], v[78:81], v[210:213], v[18:21]
	s_setprio 0
	s_setprio 1
	v_mfma_f32_16x16x32_bf16 v[34:37], v[150:153], v[178:181], v[34:37]
	v_mfma_f32_16x16x32_bf16 v[78:81], v[154:157], v[182:185], v[34:37]
	v_mfma_f32_16x16x32_bf16 v[34:37], v[158:161], v[178:181], v[38:41]
	v_mfma_f32_16x16x32_bf16 v[74:77], v[162:165], v[182:185], v[34:37]
	v_mfma_f32_16x16x32_bf16 v[34:37], v[150:153], v[190:193], v[50:53]
	v_mfma_f32_16x16x32_bf16 v[62:65], v[154:157], v[194:197], v[34:37]
	v_mfma_f32_16x16x32_bf16 v[34:37], v[158:161], v[190:193], v[54:57]
	v_mfma_f32_16x16x32_bf16 v[30:33], v[150:153], v[198:201], v[30:33]
	v_mfma_f32_16x16x32_bf16 v[26:29], v[158:161], v[198:201], v[26:29]
	v_mfma_f32_16x16x32_bf16 v[12:15], v[150:153], v[206:209], v[14:17]
	v_mfma_f32_16x16x32_bf16 v[8:11], v[158:161], v[206:209], v[8:11]
	v_mfma_f32_16x16x32_bf16 v[58:61], v[162:165], v[194:197], v[34:37]
	v_mfma_f32_16x16x32_bf16 v[30:33], v[154:157], v[202:205], v[30:33]
	v_mfma_f32_16x16x32_bf16 v[26:29], v[162:165], v[202:205], v[26:29]
	v_mfma_f32_16x16x32_bf16 v[14:17], v[154:157], v[210:213], v[12:15]
	v_mfma_f32_16x16x32_bf16 v[10:13], v[162:165], v[210:213], v[8:11]
	s_setprio 0
	s_barrier
	s_add_i32 s34, s34, 2
	s_add_u32 s4, s4, 0x100
	s_addc_u32 s5, s5, 0
	s_add_u32 s29, s29, 0x100
	s_addc_u32 s31, s31, 0
	s_cmp_gt_u32 s34, 13
	s_cbranch_scc0 .LBB0_405
	s_and_b64 vcc, exec, s[12:13]
	s_cbranch_vccz .LBB0_408
	s_barrier

; #define PG8_STAGE(bufoff, gbase, voff) do { _Pragma("unroll") for (int _i = 0; _i < 2; ++_i) \
;         __builtin_amdgcn_global_load_lds((const unsigned*)((const char*)(gbase) + (voff)[_i]), (LAS unsigned*)(lds + (bufoff) + ldsw + _i * 8192), 16, 0, 0); } while (0)
; #define PG8_LDA(dst, b, h) do { _Pragma("unroll") for (int m = 0; m < 4; ++m) _Pragma("unroll") for (int k = 0; k < 2; ++k) dst[m][k] = *(const LAS bf16x8*)(lds + PG8_SA(b, h) + aoff + m * 2048 + k * 1024); } while (0)
; #define PG8_LDB(dst, b, h) do { _Pragma("unroll") for (int n = 0; n < 2; ++n) _Pragma("unroll") for (int k = 0; k < 2; ++k) dst[n][k] = *(const LAS bf16x8*)(lds + PG8_SB(b, h) + boff + n * 2048 + k * 1024); } while (0)
; #define PG8_MMA(ai, bj, At, Bt) do { __builtin_amdgcn_s_setprio(1); _Pragma("unroll") for (int m = 0; m < 4; ++m) _Pragma("unroll") for (int n = 0; n < 2; ++n) _Pragma("unroll") for (int k = 0; k < 2; ++k) \
;         acc[ai][bj][m][n] = __builtin_amdgcn_mfma_f32_16x16x32_bf16(Bt[n][k], At[m][k], acc[ai][bj][m][n], 0, 0, 0); __builtin_amdgcn_s_setprio(0); } while (0)
; #define PG8_WAIT_V(n) asm volatile("s_waitcnt vmcnt(" #n ")" ::: "memory")
; #define PG8_WAIT_L(n) asm volatile("s_waitcnt lgkmcnt(" #n ")" ::: "memory")
; #define PG8_BAR __builtin_amdgcn_s_barrier()
; template <class Epi, class Sched, bool ALIGN_EPI>
; __device__ __forceinline__ void gemm_phase(LAS unsigned char* lds, const Gemm g, const Sched& S, const Epi& E, int wave_s) {
;     ...
;         for (int t = 0; t < nt; t += 2) {
;             const bool last = (t == nt - 2);
;             const char* a1 = cA + (size_t)(t + 1) * kstep;
;             const char* a2 = last ? nA : cA + (size_t)(t + 2) * kstep; const char* b2 = last ? nB : cB + (size_t)(t + 2) * kstep;
;             const char* a3 = a2 + kstep; const char* b3 = b2 + kstep;
;             PG8_LDB(B0, 0, 0); PG8_LDB(B1, 0, 1); PG8_SCHED; PG8_LDA(At, 0, 0); PG8_STAGE(PG8_SA(1, 1), a1 + hstepA, voffA);
;             PG8_WAIT_V(8); PG8_WAIT_L(0); PG8_BAR; PG8_MMA(0, 0, At, B0); PG8_MMA(0, 1, At, B1); PG8_BAR; PG8_SCHED;
;     ...
; #pragma unroll
;         for (int a = 0; a < 2; ++a)
; #pragma unroll
;             for (int b = 0; b < 2; ++b)
; #pragma unroll
;                 for (int m = 0; m < 4; ++m)
; #pragma unroll
;                     for (int n = 0; n < 2; ++n) acc[a][b][m][n] = (f32x4){0.f, 0.f, 0.f, 0.f};
.LBB0_615:
	s_add_u32 s4, s0, 0xfffc0080
	s_addc_u32 s5, s1, -1
	s_add_i32 s35, 0, 0x10000
	s_cmp_eq_u32 s34, 12
	s_cselect_b32 s7, s9, s5
	s_cselect_b32 s6, s23, s4
	s_cselect_b32 s5, s21, s31
	s_cselect_b32 s4, s28, s29
	s_add_i32 s86, 0, 0x14000
	v_add_u32_e32 v54, s35, v1
	v_add_u32_e32 v166, s86, v1
	ds_read_b128 v[34:37], v54
	ds_read_b128 v[38:41], v54 offset:1024
	ds_read_b128 v[50:53], v54 offset:2048
	ds_read_b128 v[54:57], v54 offset:3072
	ds_read_b128 v[158:161], v166
	ds_read_b128 v[162:165], v166 offset:1024
	ds_read_b128 v[170:173], v166 offset:2048
	ds_read_b128 v[174:177], v166 offset:3072
	v_lshl_add_u64 v[166:167], s[0:1], 0, v[154:155]
	s_add_i32 m0, s43, 0xc000
	ds_read_b128 v[178:181], v168
	ds_read_b128 v[182:185], v168 offset:1024
	ds_read_b128 v[186:189], v168 offset:2048
	ds_read_b128 v[190:193], v168 offset:3072
	ds_read_b128 v[194:197], v168 offset:4096
	ds_read_b128 v[198:201], v168 offset:5120
	ds_read_b128 v[214:217], v168 offset:6144
	ds_read_b128 v[218:221], v168 offset:7168
	global_load_lds_dwordx4 v[166:167], off
	v_lshl_add_u64 v[166:167], s[0:1], 0, v[156:157]
	s_add_i32 m0, s43, 0xe000
	s_nop 0
	global_load_lds_dwordx4 v[166:167], off
	s_cmp_lg_u32 s34, -2
	s_cbranch_scc1 .Lzacc_615_skip
	v_mov_b32_e32 v3, 0
	v_mov_b32_e32 v4, 0
	v_mov_b32_e32 v5, 0
	v_mov_b32_e32 v6, 0
	v_mov_b32_e32 v7, 0
	v_mov_b32_e32 v8, 0
	v_mov_b32_e32 v9, 0
	v_mov_b32_e32 v18, 0
	v_mov_b32_e32 v19, 0
	v_mov_b32_e32 v20, 0
	v_mov_b32_e32 v21, 0
	v_mov_b32_e32 v22, 0
	v_mov_b32_e32 v23, 0
	v_mov_b32_e32 v24, 0
	v_mov_b32_e32 v25, 0
	v_mov_b32_e32 v42, 0
	v_mov_b32_e32 v43, 0
	v_mov_b32_e32 v44, 0
	v_mov_b32_e32 v45, 0
	v_mov_b32_e32 v46, 0
	v_mov_b32_e32 v47, 0
	v_mov_b32_e32 v48, 0
	v_mov_b32_e32 v49, 0
	v_mov_b32_e32 v66, 0
	v_mov_b32_e32 v67, 0
	v_mov_b32_e32 v68, 0
	v_mov_b32_e32 v69, 0
	v_mov_b32_e32 v70, 0
	v_mov_b32_e32 v71, 0
	v_mov_b32_e32 v72, 0
	v_mov_b32_e32 v73, 0
	v_mov_b32_e32 v10, 0
	v_mov_b32_e32 v11, 0
	v_mov_b32_e32 v12, 0
	v_mov_b32_e32 v13, 0
	v_mov_b32_e32 v14, 0
	v_mov_b32_e32 v15, 0
	v_mov_b32_e32 v16, 0
	v_mov_b32_e32 v17, 0
	v_mov_b32_e32 v26, 0
	v_mov_b32_e32 v27, 0
	v_mov_b32_e32 v28, 0
	v_mov_b32_e32 v29, 0
	v_mov_b32_e32 v30, 0
	v_mov_b32_e32 v31, 0
	v_mov_b32_e32 v32, 0
	v_mov_b32_e32 v33, 0
	v_mov_b32_e32 v58, 0
	v_mov_b32_e32 v59, 0
	v_mov_b32_e32 v60, 0
	v_mov_b32_e32 v61, 0
	v_mov_b32_e32 v62, 0
	v_mov_b32_e32 v63, 0
	v_mov_b32_e32 v64, 0
	v_mov_b32_e32 v65, 0
	v_mov_b32_e32 v74, 0
	v_mov_b32_e32 v75, 0
	v_mov_b32_e32 v76, 0
	v_mov_b32_e32 v77, 0
	v_mov_b32_e32 v78, 0
	v_mov_b32_e32 v79, 0
	v_mov_b32_e32 v80, 0
	v_mov_b32_e32 v81, 0
	v_mov_b32_e32 v82, 0
	v_mov_b32_e32 v83, 0
	v_mov_b32_e32 v84, 0
	v_mov_b32_e32 v85, 0
	v_mov_b32_e32 v86, 0
	v_mov_b32_e32 v87, 0
	v_mov_b32_e32 v88, 0
	v_mov_b32_e32 v89, 0
	v_mov_b32_e32 v98, 0
	v_mov_b32_e32 v99, 0
	v_mov_b32_e32 v100, 0
	v_mov_b32_e32 v101, 0
	v_mov_b32_e32 v102, 0
	v_mov_b32_e32 v103, 0
	v_mov_b32_e32 v104, 0
	v_mov_b32_e32 v105, 0
	v_mov_b32_e32 v114, 0
	v_mov_b32_e32 v115, 0
	v_mov_b32_e32 v116, 0
	v_mov_b32_e32 v117, 0
	v_mov_b32_e32 v118, 0
	v_mov_b32_e32 v119, 0
	v_mov_b32_e32 v120, 0
	v_mov_b32_e32 v121, 0
	v_mov_b32_e32 v130, 0
	v_mov_b32_e32 v131, 0
	v_mov_b32_e32 v132, 0
	v_mov_b32_e32 v133, 0
	v_mov_b32_e32 v134, 0
	v_mov_b32_e32 v135, 0
	v_mov_b32_e32 v136, 0
	v_mov_b32_e32 v137, 0
	v_mov_b32_e32 v90, 0
	v_mov_b32_e32 v91, 0
	v_mov_b32_e32 v92, 0
	v_mov_b32_e32 v93, 0
	v_mov_b32_e32 v94, 0
	v_mov_b32_e32 v95, 0
	v_mov_b32_e32 v96, 0
	v_mov_b32_e32 v97, 0
	v_mov_b32_e32 v106, 0
	v_mov_b32_e32 v107, 0
	v_mov_b32_e32 v108, 0
	v_mov_b32_e32 v109, 0
	v_mov_b32_e32 v110, 0
	v_mov_b32_e32 v111, 0
	v_mov_b32_e32 v112, 0
	v_mov_b32_e32 v113, 0
	v_mov_b32_e32 v122, 0
	v_mov_b32_e32 v123, 0
	v_mov_b32_e32 v124, 0
	v_mov_b32_e32 v125, 0
	v_mov_b32_e32 v126, 0
	v_mov_b32_e32 v127, 0
	v_mov_b32_e32 v128, 0
	v_mov_b32_e32 v129, 0
	v_mov_b32_e32 v138, 0
	v_mov_b32_e32 v139, 0
	v_mov_b32_e32 v140, 0
	v_mov_b32_e32 v141, 0
	v_mov_b32_e32 v142, 0
	v_mov_b32_e32 v143, 0
	v_mov_b32_e32 v144, 0
	v_mov_b32_e32 v145, 0
.Lzacc_615_skip:
	s_waitcnt vmcnt(8)
	s_waitcnt lgkmcnt(0)
	s_barrier
	s_setprio 1
	s_waitcnt lgkmcnt(0)
	v_mfma_f32_16x16x32_bf16 v[142:145], v[34:37], v[178:181], v[142:145]
	v_mfma_f32_16x16x32_bf16 v[138:141], v[50:53], v[178:181], v[138:141]
	v_mfma_f32_16x16x32_bf16 v[126:129], v[34:37], v[186:189], v[126:129]
	v_mfma_f32_16x16x32_bf16 v[122:125], v[50:53], v[186:189], v[122:125]
	v_mfma_f32_16x16x32_bf16 v[110:113], v[34:37], v[194:197], v[110:113]
	v_mfma_f32_16x16x32_bf16 v[106:109], v[50:53], v[194:197], v[106:109]
	v_mfma_f32_16x16x32_bf16 v[94:97], v[34:37], v[214:217], v[94:97]
	v_mfma_f32_16x16x32_bf16 v[90:93], v[50:53], v[214:217], v[90:93]
	v_mfma_f32_16x16x32_bf16 v[142:145], v[38:41], v[182:185], v[142:145]
	v_mfma_f32_16x16x32_bf16 v[138:141], v[54:57], v[182:185], v[138:141]
	v_mfma_f32_16x16x32_bf16 v[126:129], v[38:41], v[190:193], v[126:129]
	v_mfma_f32_16x16x32_bf16 v[122:125], v[54:57], v[190:193], v[122:125]
	v_mfma_f32_16x16x32_bf16 v[110:113], v[38:41], v[198:201], v[110:113]
	v_mfma_f32_16x16x32_bf16 v[106:109], v[54:57], v[198:201], v[106:109]
	v_mfma_f32_16x16x32_bf16 v[94:97], v[38:41], v[218:221], v[94:97]
	v_mfma_f32_16x16x32_bf16 v[90:93], v[54:57], v[218:221], v[90:93]
	s_setprio 0
	s_setprio 1
	v_mfma_f32_16x16x32_bf16 v[134:137], v[158:161], v[178:181], v[134:137]
	v_mfma_f32_16x16x32_bf16 v[130:133], v[170:173], v[178:181], v[130:133]
	v_mfma_f32_16x16x32_bf16 v[118:121], v[158:161], v[186:189], v[118:121]
	v_mfma_f32_16x16x32_bf16 v[114:117], v[170:173], v[186:189], v[114:117]
	v_mfma_f32_16x16x32_bf16 v[102:105], v[158:161], v[194:197], v[102:105]
	v_mfma_f32_16x16x32_bf16 v[98:101], v[170:173], v[194:197], v[98:101]
	v_mfma_f32_16x16x32_bf16 v[86:89], v[158:161], v[214:217], v[86:89]
	v_mfma_f32_16x16x32_bf16 v[82:85], v[170:173], v[214:217], v[82:85]
	v_mfma_f32_16x16x32_bf16 v[134:137], v[162:165], v[182:185], v[134:137]
	v_mfma_f32_16x16x32_bf16 v[130:133], v[174:177], v[182:185], v[130:133]
	v_mfma_f32_16x16x32_bf16 v[118:121], v[162:165], v[190:193], v[118:121]
	v_mfma_f32_16x16x32_bf16 v[114:117], v[174:177], v[190:193], v[114:117]
	v_mfma_f32_16x16x32_bf16 v[102:105], v[162:165], v[198:201], v[102:105]
	v_mfma_f32_16x16x32_bf16 v[98:101], v[174:177], v[198:201], v[98:101]
	v_mfma_f32_16x16x32_bf16 v[86:89], v[162:165], v[218:221], v[86:89]
	v_mfma_f32_16x16x32_bf16 v[82:85], v[174:177], v[218:221], v[82:85]
	s_setprio 0
	s_barrier
; #define PG8_STAGE(bufoff, gbase, voff) do { _Pragma("unroll") for (int _i = 0; _i < 2; ++_i) \
;         __builtin_amdgcn_global_load_lds((const unsigned*)((const char*)(gbase) + (voff)[_i]), (LAS unsigned*)(lds + (bufoff) + ldsw + _i * 8192), 16, 0, 0); } while (0)
; #define PG8_LDA(dst, b, h) do { _Pragma("unroll") for (int m = 0; m < 4; ++m) _Pragma("unroll") for (int k = 0; k < 2; ++k) dst[m][k] = *(const LAS bf16x8*)(lds + PG8_SA(b, h) + aoff + m * 2048 + k * 1024); } while (0)
; #define PG8_LDB(dst, b, h) do { _Pragma("unroll") for (int n = 0; n < 2; ++n) _Pragma("unroll") for (int k = 0; k < 2; ++k) dst[n][k] = *(const LAS bf16x8*)(lds + PG8_SB(b, h) + boff + n * 2048 + k * 1024); } while (0)
; #define PG8_MMA(ai, bj, At, Bt) do { __builtin_amdgcn_s_setprio(1); _Pragma("unroll") for (int m = 0; m < 4; ++m) _Pragma("unroll") for (int n = 0; n < 2; ++n) _Pragma("unroll") for (int k = 0; k < 2; ++k) \
;         acc[ai][bj][m][n] = __builtin_amdgcn_mfma_f32_16x16x32_bf16(Bt[n][k], At[m][k], acc[ai][bj][m][n], 0, 0, 0); __builtin_amdgcn_s_setprio(0); } while (0)
; #define PG8_WAIT_V(n) asm volatile("s_waitcnt vmcnt(" #n ")" ::: "memory")
; #define PG8_WAIT_L(n) asm volatile("s_waitcnt lgkmcnt(" #n ")" ::: "memory")
; #define PG8_BAR __builtin_amdgcn_s_barrier()
; #define PG8_SCHED __builtin_amdgcn_sched_barrier(0)
; template <class Epi, class Sched, bool ALIGN_EPI>
; __device__ __forceinline__ void gemm_phase(LAS unsigned char* lds, const Gemm g, const Sched& S, const Epi& E, int wave_s) {
;     ...
;             PG8_LDA(At, 0, 1); PG8_STAGE(PG8_SB(0, 0), b2, voffB); PG8_STAGE(PG8_SB(0, 1), b2 + hstepB, voffB); PG8_STAGE(PG8_SA(0, 0), a2, voffA);
;             PG8_WAIT_V(8); PG8_WAIT_L(0); PG8_BAR; PG8_MMA(1, 0, At, B0); PG8_MMA(1, 1, At, B1); PG8_BAR; PG8_SCHED;
;             PG8_LDB(B0, 1, 0); PG8_LDB(B1, 1, 1); PG8_SCHED; PG8_LDA(At, 1, 0); PG8_STAGE(PG8_SA(0, 1), a2 + hstepA, voffA);
;             PG8_WAIT_V(8); PG8_WAIT_L(0); PG8_BAR; PG8_MMA(0, 0, At, B0); PG8_MMA(0, 1, At, B1); PG8_BAR; PG8_SCHED;
	s_add_i32 s35, s35, s42
	v_lshl_add_u64 v[166:167], s[4:5], 0, v[150:151]
	s_mov_b32 m0, s35
	ds_read_b128 v[178:181], v168 offset:16384
	ds_read_b128 v[182:185], v168 offset:17408
	ds_read_b128 v[186:189], v168 offset:18432
	ds_read_b128 v[190:193], v168 offset:19456
	ds_read_b128 v[194:197], v168 offset:20480
	ds_read_b128 v[198:201], v168 offset:21504
	ds_read_b128 v[214:217], v168 offset:22528
	ds_read_b128 v[218:221], v168 offset:23552
	global_load_lds_dwordx4 v[166:167], off
	s_add_i32 m0, s35, 0x2000
	s_add_u32 s84, s4, 0x40000
	v_lshl_add_u64 v[202:203], s[4:5], 0, v[146:147]
	s_addc_u32 s85, s5, 0
	s_add_i32 s35, s86, s42
	global_load_lds_dwordx4 v[202:203], off
	v_lshl_add_u64 v[204:205], s[84:85], 0, v[150:151]
	s_mov_b32 m0, s35
	v_lshl_add_u64 v[206:207], s[6:7], 0, v[148:149]
	global_load_lds_dwordx4 v[204:205], off
	v_lshl_add_u64 v[204:205], s[84:85], 0, v[146:147]
	s_add_i32 m0, s35, 0x2000
	s_nop 0
	global_load_lds_dwordx4 v[204:205], off
	v_lshl_add_u64 v[204:205], s[6:7], 0, v[152:153]
	s_mov_b32 m0, s43
	s_nop 0
	global_load_lds_dwordx4 v[204:205], off
	s_mov_b32 m0, s46
	s_nop 0
	global_load_lds_dwordx4 v[206:207], off
	s_waitcnt vmcnt(8)
	s_waitcnt lgkmcnt(0)
	s_barrier
	s_setprio 1
	s_waitcnt lgkmcnt(0)
	v_mfma_f32_16x16x32_bf16 v[78:81], v[34:37], v[178:181], v[78:81]
	v_mfma_f32_16x16x32_bf16 v[74:77], v[50:53], v[178:181], v[74:77]
	v_mfma_f32_16x16x32_bf16 v[62:65], v[34:37], v[186:189], v[62:65]
	v_mfma_f32_16x16x32_bf16 v[58:61], v[50:53], v[186:189], v[58:61]
	v_mfma_f32_16x16x32_bf16 v[30:33], v[34:37], v[194:197], v[30:33]
	v_mfma_f32_16x16x32_bf16 v[26:29], v[50:53], v[194:197], v[26:29]
	v_mfma_f32_16x16x32_bf16 v[14:17], v[34:37], v[214:217], v[14:17]
	v_mfma_f32_16x16x32_bf16 v[10:13], v[50:53], v[214:217], v[10:13]
	v_mfma_f32_16x16x32_bf16 v[78:81], v[38:41], v[182:185], v[78:81]
	v_mfma_f32_16x16x32_bf16 v[74:77], v[54:57], v[182:185], v[74:77]
	v_mfma_f32_16x16x32_bf16 v[62:65], v[38:41], v[190:193], v[62:65]
	v_mfma_f32_16x16x32_bf16 v[58:61], v[54:57], v[190:193], v[58:61]
	v_mfma_f32_16x16x32_bf16 v[30:33], v[38:41], v[198:201], v[30:33]
	v_mfma_f32_16x16x32_bf16 v[26:29], v[54:57], v[198:201], v[26:29]
	v_mfma_f32_16x16x32_bf16 v[14:17], v[38:41], v[218:221], v[14:17]
	v_mfma_f32_16x16x32_bf16 v[10:13], v[54:57], v[218:221], v[10:13]
	s_setprio 0
	s_setprio 1
	v_mfma_f32_16x16x32_bf16 v[46:49], v[158:161], v[186:189], v[46:49]
	v_mfma_f32_16x16x32_bf16 v[42:45], v[170:173], v[186:189], v[42:45]
	v_mfma_f32_16x16x32_bf16 v[22:25], v[158:161], v[194:197], v[22:25]
	v_mfma_f32_16x16x32_bf16 v[18:21], v[170:173], v[194:197], v[18:21]
	v_mfma_f32_16x16x32_bf16 v[6:9], v[158:161], v[214:217], v[6:9]
	v_mfma_f32_16x16x32_bf16 v[2:5], v[170:173], v[214:217], v[2:5]
	v_mfma_f32_16x16x32_bf16 v[34:37], v[158:161], v[178:181], v[70:73]
	v_mfma_f32_16x16x32_bf16 v[38:41], v[170:173], v[178:181], v[66:69]
	v_mfma_f32_16x16x32_bf16 v[46:49], v[162:165], v[190:193], v[46:49]
	v_mfma_f32_16x16x32_bf16 v[42:45], v[174:177], v[190:193], v[42:45]
	v_mfma_f32_16x16x32_bf16 v[22:25], v[162:165], v[198:201], v[22:25]
	v_mfma_f32_16x16x32_bf16 v[18:21], v[174:177], v[198:201], v[18:21]
	v_mfma_f32_16x16x32_bf16 v[6:9], v[162:165], v[218:221], v[6:9]
	v_mfma_f32_16x16x32_bf16 v[2:5], v[174:177], v[218:221], v[2:5]
	v_mfma_f32_16x16x32_bf16 v[34:37], v[162:165], v[182:185], v[34:37]
	v_mfma_f32_16x16x32_bf16 v[38:41], v[174:177], v[182:185], v[38:41]
	s_setprio 0
	s_barrier
	s_add_i32 s35, 0, 0x18000
	s_add_i32 s84, 0, 0x1c000
	v_add_u32_e32 v70, s35, v1
	v_add_u32_e32 v169, s84, v1
	ds_read_b128 v[50:53], v70
	ds_read_b128 v[54:57], v70 offset:1024
	ds_read_b128 v[66:69], v70 offset:2048
	ds_read_b128 v[70:73], v70 offset:3072
	ds_read_b128 v[158:161], v169
	ds_read_b128 v[162:165], v169 offset:1024
	ds_read_b128 v[170:173], v169 offset:2048
	ds_read_b128 v[174:177], v169 offset:3072
	s_add_u32 s6, s6, 0x40000
	s_addc_u32 s7, s7, 0
	s_mov_b32 m0, s47
	v_lshl_add_u64 v[208:209], s[6:7], 0, v[152:153]
	ds_read_b128 v[178:181], v168 offset:32768
	ds_read_b128 v[182:185], v168 offset:33792
	ds_read_b128 v[186:189], v168 offset:34816
	ds_read_b128 v[190:193], v168 offset:35840
	ds_read_b128 v[194:197], v168 offset:36864
	ds_read_b128 v[198:201], v168 offset:37888
	ds_read_b128 v[214:217], v168 offset:38912
	ds_read_b128 v[218:221], v168 offset:39936
	global_load_lds_dwordx4 v[208:209], off
	v_lshl_add_u64 v[208:209], s[6:7], 0, v[148:149]
	s_mov_b32 m0, s48
	s_nop 0
	global_load_lds_dwordx4 v[208:209], off
	s_waitcnt vmcnt(8)
	s_waitcnt lgkmcnt(0)
	s_barrier
; #define PG8_STAGE(bufoff, gbase, voff) do { _Pragma("unroll") for (int _i = 0; _i < 2; ++_i) \
;         __builtin_amdgcn_global_load_lds((const unsigned*)((const char*)(gbase) + (voff)[_i]), (LAS unsigned*)(lds + (bufoff) + ldsw + _i * 8192), 16, 0, 0); } while (0)
; #define PG8_LDA(dst, b, h) do { _Pragma("unroll") for (int m = 0; m < 4; ++m) _Pragma("unroll") for (int k = 0; k < 2; ++k) dst[m][k] = *(const LAS bf16x8*)(lds + PG8_SA(b, h) + aoff + m * 2048 + k * 1024); } while (0)
; #define PG8_MMA(ai, bj, At, Bt) do { __builtin_amdgcn_s_setprio(1); _Pragma("unroll") for (int m = 0; m < 4; ++m) _Pragma("unroll") for (int n = 0; n < 2; ++n) _Pragma("unroll") for (int k = 0; k < 2; ++k) \
;         acc[ai][bj][m][n] = __builtin_amdgcn_mfma_f32_16x16x32_bf16(Bt[n][k], At[m][k], acc[ai][bj][m][n], 0, 0, 0); __builtin_amdgcn_s_setprio(0); } while (0)
; #define PG8_WAIT_V(n) asm volatile("s_waitcnt vmcnt(" #n ")" ::: "memory")
; #define PG8_WAIT_L(n) asm volatile("s_waitcnt lgkmcnt(" #n ")" ::: "memory")
; #define PG8_BAR __builtin_amdgcn_s_barrier()
; #define PG8_SCHED __builtin_amdgcn_sched_barrier(0)
; template <class Epi, class Sched, bool ALIGN_EPI>
; __device__ __forceinline__ void gemm_phase(LAS unsigned char* lds, const Gemm g, const Sched& S, const Epi& E, int wave_s) {
;     ...
;             PG8_WAIT_V(8); PG8_WAIT_L(0); PG8_BAR; PG8_MMA(0, 0, At, B0); PG8_MMA(0, 1, At, B1); PG8_BAR; PG8_SCHED;
;             PG8_LDA(At, 1, 1); PG8_STAGE(PG8_SB(1, 0), b3, voffB); PG8_STAGE(PG8_SB(1, 1), b3 + hstepB, voffB); PG8_STAGE(PG8_SA(1, 0), a3, voffA);
;             PG8_WAIT_V(8); PG8_WAIT_L(0); PG8_BAR; PG8_MMA(1, 0, At, B0); PG8_MMA(1, 1, At, B1); PG8_BAR; PG8_SCHED;
;         }
;         if constexpr (ALIGN_EPI) { if (wr == 0) PG8_BAR; }
;         E(acc, cur, wr, wc, fr, fq);
;         if (!has_next) break;
	s_setprio 1
	s_waitcnt lgkmcnt(0)
	v_mfma_f32_16x16x32_bf16 v[142:145], v[50:53], v[178:181], v[142:145]
	v_mfma_f32_16x16x32_bf16 v[138:141], v[66:69], v[178:181], v[138:141]
	v_mfma_f32_16x16x32_bf16 v[126:129], v[50:53], v[186:189], v[126:129]
	v_mfma_f32_16x16x32_bf16 v[122:125], v[66:69], v[186:189], v[122:125]
	v_mfma_f32_16x16x32_bf16 v[110:113], v[50:53], v[194:197], v[110:113]
	v_mfma_f32_16x16x32_bf16 v[106:109], v[66:69], v[194:197], v[106:109]
	v_mfma_f32_16x16x32_bf16 v[94:97], v[50:53], v[214:217], v[94:97]
	v_mfma_f32_16x16x32_bf16 v[90:93], v[66:69], v[214:217], v[90:93]
	v_mfma_f32_16x16x32_bf16 v[142:145], v[54:57], v[182:185], v[142:145]
	v_mfma_f32_16x16x32_bf16 v[138:141], v[70:73], v[182:185], v[138:141]
	v_mfma_f32_16x16x32_bf16 v[126:129], v[54:57], v[190:193], v[126:129]
	v_mfma_f32_16x16x32_bf16 v[122:125], v[70:73], v[190:193], v[122:125]
	v_mfma_f32_16x16x32_bf16 v[110:113], v[54:57], v[198:201], v[110:113]
	v_mfma_f32_16x16x32_bf16 v[106:109], v[70:73], v[198:201], v[106:109]
	v_mfma_f32_16x16x32_bf16 v[94:97], v[54:57], v[218:221], v[94:97]
	v_mfma_f32_16x16x32_bf16 v[90:93], v[70:73], v[218:221], v[90:93]
	s_setprio 0
	s_setprio 1
	v_mfma_f32_16x16x32_bf16 v[134:137], v[158:161], v[178:181], v[134:137]
	v_mfma_f32_16x16x32_bf16 v[130:133], v[170:173], v[178:181], v[130:133]
	v_mfma_f32_16x16x32_bf16 v[118:121], v[158:161], v[186:189], v[118:121]
	v_mfma_f32_16x16x32_bf16 v[114:117], v[170:173], v[186:189], v[114:117]
	v_mfma_f32_16x16x32_bf16 v[102:105], v[158:161], v[194:197], v[102:105]
	v_mfma_f32_16x16x32_bf16 v[98:101], v[170:173], v[194:197], v[98:101]
	v_mfma_f32_16x16x32_bf16 v[86:89], v[158:161], v[214:217], v[86:89]
	v_mfma_f32_16x16x32_bf16 v[82:85], v[170:173], v[214:217], v[82:85]
	v_mfma_f32_16x16x32_bf16 v[134:137], v[162:165], v[182:185], v[134:137]
	v_mfma_f32_16x16x32_bf16 v[130:133], v[174:177], v[182:185], v[130:133]
	v_mfma_f32_16x16x32_bf16 v[118:121], v[162:165], v[190:193], v[118:121]
	v_mfma_f32_16x16x32_bf16 v[114:117], v[174:177], v[190:193], v[114:117]
	v_mfma_f32_16x16x32_bf16 v[102:105], v[162:165], v[198:201], v[102:105]
	v_mfma_f32_16x16x32_bf16 v[98:101], v[174:177], v[198:201], v[98:101]
	v_mfma_f32_16x16x32_bf16 v[86:89], v[162:165], v[218:221], v[86:89]
	v_mfma_f32_16x16x32_bf16 v[82:85], v[174:177], v[218:221], v[82:85]
	s_setprio 0
	s_barrier
	s_add_i32 s6, s35, s42
	v_lshl_add_u64 v[166:167], v[166:167], 0, s[74:75]
	s_mov_b32 m0, s6
	ds_read_b128 v[178:181], v168 offset:49152
	ds_read_b128 v[182:185], v168 offset:50176
	ds_read_b128 v[186:189], v168 offset:51200
	ds_read_b128 v[190:193], v168 offset:52224
	ds_read_b128 v[194:197], v168 offset:53248
	ds_read_b128 v[198:201], v168 offset:54272
	ds_read_b128 v[214:217], v168 offset:55296
	ds_read_b128 v[218:221], v168 offset:56320
	global_load_lds_dwordx4 v[166:167], off
	s_add_i32 m0, s6, 0x2000
	s_add_u32 s4, s4, 0x40080
	v_lshl_add_u64 v[166:167], v[202:203], 0, s[74:75]
	s_addc_u32 s5, s5, 0
	s_add_i32 s6, s84, s42
	global_load_lds_dwordx4 v[166:167], off
	v_lshl_add_u64 v[166:167], s[4:5], 0, v[150:151]
	s_mov_b32 m0, s6
	s_nop 0
	global_load_lds_dwordx4 v[166:167], off
	v_lshl_add_u64 v[166:167], s[4:5], 0, v[146:147]
	s_add_i32 m0, s6, 0x2000
	s_nop 0
	global_load_lds_dwordx4 v[166:167], off
	v_lshl_add_u64 v[166:167], v[204:205], 0, s[74:75]
	s_mov_b32 m0, s51
	s_nop 0
	global_load_lds_dwordx4 v[166:167], off
	v_lshl_add_u64 v[166:167], v[206:207], 0, s[74:75]
	s_mov_b32 m0, s81
	s_nop 0
	global_load_lds_dwordx4 v[166:167], off
	s_waitcnt vmcnt(8)
	s_waitcnt lgkmcnt(0)
	s_barrier
	s_setprio 1
	s_waitcnt lgkmcnt(0)
	v_mfma_f32_16x16x32_bf16 v[78:81], v[50:53], v[178:181], v[78:81]
	v_mfma_f32_16x16x32_bf16 v[74:77], v[66:69], v[178:181], v[74:77]
	v_mfma_f32_16x16x32_bf16 v[62:65], v[50:53], v[186:189], v[62:65]
	v_mfma_f32_16x16x32_bf16 v[58:61], v[66:69], v[186:189], v[58:61]
	v_mfma_f32_16x16x32_bf16 v[30:33], v[50:53], v[194:197], v[30:33]
	v_mfma_f32_16x16x32_bf16 v[26:29], v[66:69], v[194:197], v[26:29]
	v_mfma_f32_16x16x32_bf16 v[14:17], v[50:53], v[214:217], v[14:17]
	v_mfma_f32_16x16x32_bf16 v[10:13], v[66:69], v[214:217], v[10:13]
	v_mfma_f32_16x16x32_bf16 v[78:81], v[54:57], v[182:185], v[78:81]
	v_mfma_f32_16x16x32_bf16 v[74:77], v[70:73], v[182:185], v[74:77]
	v_mfma_f32_16x16x32_bf16 v[62:65], v[54:57], v[190:193], v[62:65]
	v_mfma_f32_16x16x32_bf16 v[58:61], v[70:73], v[190:193], v[58:61]
	v_mfma_f32_16x16x32_bf16 v[30:33], v[54:57], v[198:201], v[30:33]
	v_mfma_f32_16x16x32_bf16 v[26:29], v[70:73], v[198:201], v[26:29]
	v_mfma_f32_16x16x32_bf16 v[14:17], v[54:57], v[218:221], v[14:17]
	v_mfma_f32_16x16x32_bf16 v[10:13], v[70:73], v[218:221], v[10:13]
	s_setprio 0
	s_setprio 1
	v_mfma_f32_16x16x32_bf16 v[34:37], v[158:161], v[178:181], v[34:37]
	v_mfma_f32_16x16x32_bf16 v[70:73], v[162:165], v[182:185], v[34:37]
	v_mfma_f32_16x16x32_bf16 v[34:37], v[170:173], v[178:181], v[38:41]
	v_mfma_f32_16x16x32_bf16 v[66:69], v[174:177], v[182:185], v[34:37]
	v_mfma_f32_16x16x32_bf16 v[34:37], v[158:161], v[186:189], v[46:49]
	v_mfma_f32_16x16x32_bf16 v[46:49], v[162:165], v[190:193], v[34:37]
	v_mfma_f32_16x16x32_bf16 v[34:37], v[170:173], v[186:189], v[42:45]
	v_mfma_f32_16x16x32_bf16 v[22:25], v[158:161], v[194:197], v[22:25]
	v_mfma_f32_16x16x32_bf16 v[18:21], v[170:173], v[194:197], v[18:21]
	v_mfma_f32_16x16x32_bf16 v[6:9], v[158:161], v[214:217], v[6:9]
	v_mfma_f32_16x16x32_bf16 v[2:5], v[170:173], v[214:217], v[2:5]
	v_mfma_f32_16x16x32_bf16 v[42:45], v[174:177], v[190:193], v[34:37]
	v_mfma_f32_16x16x32_bf16 v[22:25], v[162:165], v[198:201], v[22:25]
	v_mfma_f32_16x16x32_bf16 v[18:21], v[174:177], v[198:201], v[18:21]
	v_mfma_f32_16x16x32_bf16 v[6:9], v[162:165], v[218:221], v[6:9]
	v_mfma_f32_16x16x32_bf16 v[2:5], v[174:177], v[218:221], v[2:5]
	s_setprio 0
	s_barrier
	s_add_i32 s34, s34, 2
	s_add_u32 s0, s0, 0x100
	s_addc_u32 s1, s1, 0
	s_add_u32 s29, s29, 0x100
	s_addc_u32 s31, s31, 0
	s_cmp_gt_u32 s34, 13
	s_cbranch_scc0 .LBB0_615
	s_and_b64 vcc, exec, s[18:19]
	s_cbranch_vccz .LBB0_618
	s_barrier

; #define PG8_STAGE(bufoff, gbase, voff) do { _Pragma("unroll") for (int _i = 0; _i < 2; ++_i) \
;         __builtin_amdgcn_global_load_lds((const unsigned*)((const char*)(gbase) + (voff)[_i]), (LAS unsigned*)(lds + (bufoff) + ldsw + _i * 8192), 16, 0, 0); } while (0)
; #define PG8_LDA(dst, b, h) do { _Pragma("unroll") for (int m = 0; m < 4; ++m) _Pragma("unroll") for (int k = 0; k < 2; ++k) dst[m][k] = *(const LAS bf16x8*)(lds + PG8_SA(b, h) + aoff + m * 2048 + k * 1024); } while (0)
; #define PG8_LDB(dst, b, h) do { _Pragma("unroll") for (int n = 0; n < 2; ++n) _Pragma("unroll") for (int k = 0; k < 2; ++k) dst[n][k] = *(const LAS bf16x8*)(lds + PG8_SB(b, h) + boff + n * 2048 + k * 1024); } while (0)
; #define PG8_MMA(ai, bj, At, Bt) do { __builtin_amdgcn_s_setprio(1); _Pragma("unroll") for (int m = 0; m < 4; ++m) _Pragma("unroll") for (int n = 0; n < 2; ++n) _Pragma("unroll") for (int k = 0; k < 2; ++k) \
;         acc[ai][bj][m][n] = __builtin_amdgcn_mfma_f32_16x16x32_bf16(Bt[n][k], At[m][k], acc[ai][bj][m][n], 0, 0, 0); __builtin_amdgcn_s_setprio(0); } while (0)
; #define PG8_WAIT_V(n) asm volatile("s_waitcnt vmcnt(" #n ")" ::: "memory")
; #define PG8_WAIT_L(n) asm volatile("s_waitcnt lgkmcnt(" #n ")" ::: "memory")
; #define PG8_BAR __builtin_amdgcn_s_barrier()
; template <class Epi, class Sched, bool ALIGN_EPI>
; __device__ __forceinline__ void gemm_phase(LAS unsigned char* lds, const Gemm g, const Sched& S, const Epi& E, int wave_s) {
;     ...
;         for (int t = 0; t < nt; t += 2) {
;             const bool last = (t == nt - 2);
;             const char* a1 = cA + (size_t)(t + 1) * kstep;
;             const char* a2 = last ? nA : cA + (size_t)(t + 2) * kstep; const char* b2 = last ? nB : cB + (size_t)(t + 2) * kstep;
;             const char* a3 = a2 + kstep; const char* b3 = b2 + kstep;
;             PG8_LDB(B0, 0, 0); PG8_LDB(B1, 0, 1); PG8_SCHED; PG8_LDA(At, 0, 0); PG8_STAGE(PG8_SA(1, 1), a1 + hstepA, voffA);
;             PG8_WAIT_V(8); PG8_WAIT_L(0); PG8_BAR; PG8_MMA(0, 0, At, B0); PG8_MMA(0, 1, At, B1); PG8_BAR; PG8_SCHED;
;     ...
; #pragma unroll
;         for (int a = 0; a < 2; ++a)
; #pragma unroll
;             for (int b = 0; b < 2; ++b)
; #pragma unroll
;                 for (int m = 0; m < 4; ++m)
; #pragma unroll
;                     for (int n = 0; n < 2; ++n) acc[a][b][m][n] = (f32x4){0.f, 0.f, 0.f, 0.f};
.LBB0_1490:
	s_add_u32 s36, s34, 0xfffc0080
	s_addc_u32 s37, s35, -1
	s_add_i32 s95, 0, 0x10000
	s_cmp_eq_u32 s94, 12
	s_cselect_b32 s39, s23, s37
	s_cselect_b32 s38, s29, s36
	s_cselect_b32 s37, s21, s93
	s_cselect_b32 s36, s91, s92
	s_add_i32 s4, 0, 0x14000
	v_add_u32_e32 v142, s95, v1
	v_add_u32_e32 v170, s4, v1
	ds_read_b128 v[130:133], v142
	ds_read_b128 v[134:137], v142 offset:1024
	ds_read_b128 v[138:141], v142 offset:2048
	ds_read_b128 v[142:145], v142 offset:3072
	ds_read_b128 v[158:161], v170
	ds_read_b128 v[162:165], v170 offset:1024
	ds_read_b128 v[166:169], v170 offset:2048
	ds_read_b128 v[170:173], v170 offset:3072
	v_lshl_add_u64 v[208:209], s[34:35], 0, v[154:155]
	s_add_i32 m0, s31, 0xc000
	ds_read_b128 v[176:179], v174
	ds_read_b128 v[180:183], v174 offset:1024
	ds_read_b128 v[184:187], v174 offset:2048
	ds_read_b128 v[188:191], v174 offset:3072
	ds_read_b128 v[192:195], v174 offset:4096
	ds_read_b128 v[196:199], v174 offset:5120
	ds_read_b128 v[200:203], v174 offset:6144
	ds_read_b128 v[204:207], v174 offset:7168
	global_load_lds_dwordx4 v[208:209], off
	v_lshl_add_u64 v[208:209], s[34:35], 0, v[156:157]
	s_add_i32 m0, s31, 0xe000
	s_nop 0
	global_load_lds_dwordx4 v[208:209], off
	s_cmp_lg_u32 s94, -2
	s_cbranch_scc1 .Lzacc_1490_skip
	v_mov_b32_e32 v3, 0
	v_mov_b32_e32 v4, 0
	v_mov_b32_e32 v5, 0
	v_mov_b32_e32 v6, 0
	v_mov_b32_e32 v7, 0
	v_mov_b32_e32 v8, 0
	v_mov_b32_e32 v9, 0
	v_mov_b32_e32 v18, 0
	v_mov_b32_e32 v19, 0
	v_mov_b32_e32 v20, 0
	v_mov_b32_e32 v21, 0
	v_mov_b32_e32 v22, 0
	v_mov_b32_e32 v23, 0
	v_mov_b32_e32 v24, 0
	v_mov_b32_e32 v25, 0
	v_mov_b32_e32 v34, 0
	v_mov_b32_e32 v35, 0
	v_mov_b32_e32 v36, 0
	v_mov_b32_e32 v37, 0
	v_mov_b32_e32 v38, 0
	v_mov_b32_e32 v39, 0
	v_mov_b32_e32 v40, 0
	v_mov_b32_e32 v41, 0
	v_mov_b32_e32 v50, 0
	v_mov_b32_e32 v51, 0
	v_mov_b32_e32 v52, 0
	v_mov_b32_e32 v53, 0
	v_mov_b32_e32 v54, 0
	v_mov_b32_e32 v55, 0
	v_mov_b32_e32 v56, 0
	v_mov_b32_e32 v57, 0
	v_mov_b32_e32 v10, 0
	v_mov_b32_e32 v11, 0
	v_mov_b32_e32 v12, 0
	v_mov_b32_e32 v13, 0
	v_mov_b32_e32 v14, 0
	v_mov_b32_e32 v15, 0
	v_mov_b32_e32 v16, 0
	v_mov_b32_e32 v17, 0
	v_mov_b32_e32 v26, 0
	v_mov_b32_e32 v27, 0
	v_mov_b32_e32 v28, 0
	v_mov_b32_e32 v29, 0
	v_mov_b32_e32 v30, 0
	v_mov_b32_e32 v31, 0
	v_mov_b32_e32 v32, 0
	v_mov_b32_e32 v33, 0
	v_mov_b32_e32 v42, 0
	v_mov_b32_e32 v43, 0
	v_mov_b32_e32 v44, 0
	v_mov_b32_e32 v45, 0
	v_mov_b32_e32 v46, 0
	v_mov_b32_e32 v47, 0
	v_mov_b32_e32 v48, 0
	v_mov_b32_e32 v49, 0
	v_mov_b32_e32 v58, 0
	v_mov_b32_e32 v59, 0
	v_mov_b32_e32 v60, 0
	v_mov_b32_e32 v61, 0
	v_mov_b32_e32 v62, 0
	v_mov_b32_e32 v63, 0
	v_mov_b32_e32 v64, 0
	v_mov_b32_e32 v65, 0
	v_mov_b32_e32 v66, 0
	v_mov_b32_e32 v67, 0
	v_mov_b32_e32 v68, 0
	v_mov_b32_e32 v69, 0
	v_mov_b32_e32 v70, 0
	v_mov_b32_e32 v71, 0
	v_mov_b32_e32 v72, 0
	v_mov_b32_e32 v73, 0
	v_mov_b32_e32 v82, 0
	v_mov_b32_e32 v83, 0
	v_mov_b32_e32 v84, 0
	v_mov_b32_e32 v85, 0
	v_mov_b32_e32 v86, 0
	v_mov_b32_e32 v87, 0
	v_mov_b32_e32 v88, 0
	v_mov_b32_e32 v89, 0
	v_mov_b32_e32 v98, 0
	v_mov_b32_e32 v99, 0
	v_mov_b32_e32 v100, 0
	v_mov_b32_e32 v101, 0
	v_mov_b32_e32 v102, 0
	v_mov_b32_e32 v103, 0
	v_mov_b32_e32 v104, 0
	v_mov_b32_e32 v105, 0
	v_mov_b32_e32 v114, 0
	v_mov_b32_e32 v115, 0
	v_mov_b32_e32 v116, 0
	v_mov_b32_e32 v117, 0
	v_mov_b32_e32 v118, 0
	v_mov_b32_e32 v119, 0
	v_mov_b32_e32 v120, 0
	v_mov_b32_e32 v121, 0
	v_mov_b32_e32 v74, 0
	v_mov_b32_e32 v75, 0
	v_mov_b32_e32 v76, 0
	v_mov_b32_e32 v77, 0
	v_mov_b32_e32 v78, 0
	v_mov_b32_e32 v79, 0
	v_mov_b32_e32 v80, 0
	v_mov_b32_e32 v81, 0
	v_mov_b32_e32 v90, 0
	v_mov_b32_e32 v91, 0
	v_mov_b32_e32 v92, 0
	v_mov_b32_e32 v93, 0
	v_mov_b32_e32 v94, 0
	v_mov_b32_e32 v95, 0
	v_mov_b32_e32 v96, 0
	v_mov_b32_e32 v97, 0
	v_mov_b32_e32 v106, 0
	v_mov_b32_e32 v107, 0
	v_mov_b32_e32 v108, 0
	v_mov_b32_e32 v109, 0
	v_mov_b32_e32 v110, 0
	v_mov_b32_e32 v111, 0
	v_mov_b32_e32 v112, 0
	v_mov_b32_e32 v113, 0
	v_mov_b32_e32 v122, 0
	v_mov_b32_e32 v123, 0
	v_mov_b32_e32 v124, 0
	v_mov_b32_e32 v125, 0
	v_mov_b32_e32 v126, 0
	v_mov_b32_e32 v127, 0
	v_mov_b32_e32 v128, 0
	v_mov_b32_e32 v129, 0
.Lzacc_1490_skip:
	s_waitcnt vmcnt(8)
	s_waitcnt lgkmcnt(0)
	s_barrier
	s_setprio 1
	s_waitcnt lgkmcnt(0)
	v_mfma_f32_16x16x32_bf16 v[126:129], v[130:133], v[176:179], v[126:129]
	v_mfma_f32_16x16x32_bf16 v[122:125], v[138:141], v[176:179], v[122:125]
	v_mfma_f32_16x16x32_bf16 v[110:113], v[130:133], v[184:187], v[110:113]
	v_mfma_f32_16x16x32_bf16 v[106:109], v[138:141], v[184:187], v[106:109]
	v_mfma_f32_16x16x32_bf16 v[94:97], v[130:133], v[192:195], v[94:97]
	v_mfma_f32_16x16x32_bf16 v[90:93], v[138:141], v[192:195], v[90:93]
	v_mfma_f32_16x16x32_bf16 v[78:81], v[130:133], v[200:203], v[78:81]
	v_mfma_f32_16x16x32_bf16 v[74:77], v[138:141], v[200:203], v[74:77]
	v_mfma_f32_16x16x32_bf16 v[126:129], v[134:137], v[180:183], v[126:129]
	v_mfma_f32_16x16x32_bf16 v[122:125], v[142:145], v[180:183], v[122:125]
	v_mfma_f32_16x16x32_bf16 v[110:113], v[134:137], v[188:191], v[110:113]
	v_mfma_f32_16x16x32_bf16 v[106:109], v[142:145], v[188:191], v[106:109]
	v_mfma_f32_16x16x32_bf16 v[94:97], v[134:137], v[196:199], v[94:97]
	v_mfma_f32_16x16x32_bf16 v[90:93], v[142:145], v[196:199], v[90:93]
	v_mfma_f32_16x16x32_bf16 v[78:81], v[134:137], v[204:207], v[78:81]
	v_mfma_f32_16x16x32_bf16 v[74:77], v[142:145], v[204:207], v[74:77]
	s_setprio 0
	s_setprio 1
	v_mfma_f32_16x16x32_bf16 v[118:121], v[158:161], v[176:179], v[118:121]
	v_mfma_f32_16x16x32_bf16 v[114:117], v[166:169], v[176:179], v[114:117]
	v_mfma_f32_16x16x32_bf16 v[102:105], v[158:161], v[184:187], v[102:105]
	v_mfma_f32_16x16x32_bf16 v[98:101], v[166:169], v[184:187], v[98:101]
	v_mfma_f32_16x16x32_bf16 v[86:89], v[158:161], v[192:195], v[86:89]
	v_mfma_f32_16x16x32_bf16 v[82:85], v[166:169], v[192:195], v[82:85]
	v_mfma_f32_16x16x32_bf16 v[70:73], v[158:161], v[200:203], v[70:73]
	v_mfma_f32_16x16x32_bf16 v[66:69], v[166:169], v[200:203], v[66:69]
	v_mfma_f32_16x16x32_bf16 v[118:121], v[162:165], v[180:183], v[118:121]
	v_mfma_f32_16x16x32_bf16 v[114:117], v[170:173], v[180:183], v[114:117]
	v_mfma_f32_16x16x32_bf16 v[102:105], v[162:165], v[188:191], v[102:105]
	v_mfma_f32_16x16x32_bf16 v[98:101], v[170:173], v[188:191], v[98:101]
	v_mfma_f32_16x16x32_bf16 v[86:89], v[162:165], v[196:199], v[86:89]
	v_mfma_f32_16x16x32_bf16 v[82:85], v[170:173], v[196:199], v[82:85]
	v_mfma_f32_16x16x32_bf16 v[70:73], v[162:165], v[204:207], v[70:73]
	v_mfma_f32_16x16x32_bf16 v[66:69], v[170:173], v[204:207], v[66:69]
	s_setprio 0
	s_barrier
; #define PG8_STAGE(bufoff, gbase, voff) do { _Pragma("unroll") for (int _i = 0; _i < 2; ++_i) \
;         __builtin_amdgcn_global_load_lds((const unsigned*)((const char*)(gbase) + (voff)[_i]), (LAS unsigned*)(lds + (bufoff) + ldsw + _i * 8192), 16, 0, 0); } while (0)
; #define PG8_LDA(dst, b, h) do { _Pragma("unroll") for (int m = 0; m < 4; ++m) _Pragma("unroll") for (int k = 0; k < 2; ++k) dst[m][k] = *(const LAS bf16x8*)(lds + PG8_SA(b, h) + aoff + m * 2048 + k * 1024); } while (0)
; #define PG8_LDB(dst, b, h) do { _Pragma("unroll") for (int n = 0; n < 2; ++n) _Pragma("unroll") for (int k = 0; k < 2; ++k) dst[n][k] = *(const LAS bf16x8*)(lds + PG8_SB(b, h) + boff + n * 2048 + k * 1024); } while (0)
; #define PG8_MMA(ai, bj, At, Bt) do { __builtin_amdgcn_s_setprio(1); _Pragma("unroll") for (int m = 0; m < 4; ++m) _Pragma("unroll") for (int n = 0; n < 2; ++n) _Pragma("unroll") for (int k = 0; k < 2; ++k) \
;         acc[ai][bj][m][n] = __builtin_amdgcn_mfma_f32_16x16x32_bf16(Bt[n][k], At[m][k], acc[ai][bj][m][n], 0, 0, 0); __builtin_amdgcn_s_setprio(0); } while (0)
; #define PG8_WAIT_V(n) asm volatile("s_waitcnt vmcnt(" #n ")" ::: "memory")
; #define PG8_WAIT_L(n) asm volatile("s_waitcnt lgkmcnt(" #n ")" ::: "memory")
; #define PG8_BAR __builtin_amdgcn_s_barrier()
; #define PG8_SCHED __builtin_amdgcn_sched_barrier(0)
; template <class Epi, class Sched, bool ALIGN_EPI>
; __device__ __forceinline__ void gemm_phase(LAS unsigned char* lds, const Gemm g, const Sched& S, const Epi& E, int wave_s) {
;     ...
;             PG8_LDA(At, 0, 1); PG8_STAGE(PG8_SB(0, 0), b2, voffB); PG8_STAGE(PG8_SB(0, 1), b2 + hstepB, voffB); PG8_STAGE(PG8_SA(0, 0), a2, voffA);
;             PG8_WAIT_V(8); PG8_WAIT_L(0); PG8_BAR; PG8_MMA(1, 0, At, B0); PG8_MMA(1, 1, At, B1); PG8_BAR; PG8_SCHED;
;             PG8_LDB(B0, 1, 0); PG8_LDB(B1, 1, 1); PG8_SCHED; PG8_LDA(At, 1, 0); PG8_STAGE(PG8_SA(0, 1), a2 + hstepA, voffA);
;             PG8_WAIT_V(8); PG8_WAIT_L(0); PG8_BAR; PG8_MMA(0, 0, At, B0); PG8_MMA(0, 1, At, B1); PG8_BAR; PG8_SCHED;
	s_add_i32 s5, s95, s43
	v_lshl_add_u64 v[208:209], s[36:37], 0, v[150:151]
	s_mov_b32 m0, s5
	ds_read_b128 v[176:179], v174 offset:16384
	ds_read_b128 v[180:183], v174 offset:17408
	ds_read_b128 v[184:187], v174 offset:18432
	ds_read_b128 v[188:191], v174 offset:19456
	ds_read_b128 v[192:195], v174 offset:20480
	ds_read_b128 v[196:199], v174 offset:21504
	ds_read_b128 v[200:203], v174 offset:22528
	ds_read_b128 v[204:207], v174 offset:23552
	global_load_lds_dwordx4 v[208:209], off
	s_add_i32 m0, s5, 0x2000
	s_add_u32 vcc_lo, s36, 0x40000
	v_lshl_add_u64 v[210:211], s[36:37], 0, v[146:147]
	s_addc_u32 vcc_hi, s37, 0
	s_add_i32 s4, s4, s43
	global_load_lds_dwordx4 v[210:211], off
	v_lshl_add_u64 v[212:213], vcc, 0, v[150:151]
	s_mov_b32 m0, s4
	v_lshl_add_u64 v[214:215], s[38:39], 0, v[148:149]
	global_load_lds_dwordx4 v[212:213], off
	v_lshl_add_u64 v[212:213], vcc, 0, v[146:147]
	s_add_i32 m0, s4, 0x2000
	s_nop 0
	global_load_lds_dwordx4 v[212:213], off
	v_lshl_add_u64 v[212:213], s[38:39], 0, v[152:153]
	s_mov_b32 m0, s31
	s_nop 0
	global_load_lds_dwordx4 v[212:213], off
	s_mov_b32 m0, s82
	s_nop 0
	global_load_lds_dwordx4 v[214:215], off
	s_waitcnt vmcnt(8)
	s_waitcnt lgkmcnt(0)
	s_barrier
	s_setprio 1
	s_waitcnt lgkmcnt(0)
	v_mfma_f32_16x16x32_bf16 v[62:65], v[130:133], v[176:179], v[62:65]
	v_mfma_f32_16x16x32_bf16 v[58:61], v[138:141], v[176:179], v[58:61]
	v_mfma_f32_16x16x32_bf16 v[46:49], v[130:133], v[184:187], v[46:49]
	v_mfma_f32_16x16x32_bf16 v[42:45], v[138:141], v[184:187], v[42:45]
	v_mfma_f32_16x16x32_bf16 v[30:33], v[130:133], v[192:195], v[30:33]
	v_mfma_f32_16x16x32_bf16 v[26:29], v[138:141], v[192:195], v[26:29]
	v_mfma_f32_16x16x32_bf16 v[14:17], v[130:133], v[200:203], v[14:17]
	v_mfma_f32_16x16x32_bf16 v[10:13], v[138:141], v[200:203], v[10:13]
	v_mfma_f32_16x16x32_bf16 v[62:65], v[134:137], v[180:183], v[62:65]
	v_mfma_f32_16x16x32_bf16 v[58:61], v[142:145], v[180:183], v[58:61]
	v_mfma_f32_16x16x32_bf16 v[46:49], v[134:137], v[188:191], v[46:49]
	v_mfma_f32_16x16x32_bf16 v[42:45], v[142:145], v[188:191], v[42:45]
	v_mfma_f32_16x16x32_bf16 v[30:33], v[134:137], v[196:199], v[30:33]
	v_mfma_f32_16x16x32_bf16 v[26:29], v[142:145], v[196:199], v[26:29]
	v_mfma_f32_16x16x32_bf16 v[14:17], v[134:137], v[204:207], v[14:17]
	v_mfma_f32_16x16x32_bf16 v[10:13], v[142:145], v[204:207], v[10:13]
	s_setprio 0
	s_setprio 1
	v_mfma_f32_16x16x32_bf16 v[54:57], v[158:161], v[176:179], v[54:57]
	v_mfma_f32_16x16x32_bf16 v[50:53], v[166:169], v[176:179], v[50:53]
	v_mfma_f32_16x16x32_bf16 v[38:41], v[158:161], v[184:187], v[38:41]
	v_mfma_f32_16x16x32_bf16 v[34:37], v[166:169], v[184:187], v[34:37]
	v_mfma_f32_16x16x32_bf16 v[22:25], v[158:161], v[192:195], v[22:25]
	v_mfma_f32_16x16x32_bf16 v[18:21], v[166:169], v[192:195], v[18:21]
	v_mfma_f32_16x16x32_bf16 v[6:9], v[158:161], v[200:203], v[6:9]
	v_mfma_f32_16x16x32_bf16 v[2:5], v[166:169], v[200:203], v[2:5]
	v_mfma_f32_16x16x32_bf16 v[54:57], v[162:165], v[180:183], v[54:57]
	v_mfma_f32_16x16x32_bf16 v[50:53], v[170:173], v[180:183], v[50:53]
	v_mfma_f32_16x16x32_bf16 v[38:41], v[162:165], v[188:191], v[38:41]
	v_mfma_f32_16x16x32_bf16 v[34:37], v[170:173], v[188:191], v[34:37]
	v_mfma_f32_16x16x32_bf16 v[22:25], v[162:165], v[196:199], v[22:25]
	v_mfma_f32_16x16x32_bf16 v[18:21], v[170:173], v[196:199], v[18:21]
	v_mfma_f32_16x16x32_bf16 v[6:9], v[162:165], v[204:207], v[6:9]
	v_mfma_f32_16x16x32_bf16 v[2:5], v[170:173], v[204:207], v[2:5]
	s_setprio 0
	s_barrier
	s_add_i32 s4, 0, 0x18000
	s_add_i32 s5, 0, 0x1c000
	v_add_u32_e32 v142, s4, v1
	v_add_u32_e32 v170, s5, v1
	ds_read_b128 v[130:133], v142
	ds_read_b128 v[134:137], v142 offset:1024
	ds_read_b128 v[138:141], v142 offset:2048
	ds_read_b128 v[142:145], v142 offset:3072
	ds_read_b128 v[158:161], v170
	ds_read_b128 v[162:165], v170 offset:1024
	ds_read_b128 v[166:169], v170 offset:2048
	ds_read_b128 v[170:173], v170 offset:3072
	s_add_u32 s38, s38, 0x40000
	s_addc_u32 s39, s39, 0
	s_mov_b32 m0, s83
	v_lshl_add_u64 v[216:217], s[38:39], 0, v[152:153]
	ds_read_b128 v[176:179], v174 offset:32768
	ds_read_b128 v[180:183], v174 offset:33792
	ds_read_b128 v[184:187], v174 offset:34816
	ds_read_b128 v[188:191], v174 offset:35840
	ds_read_b128 v[192:195], v174 offset:36864
	ds_read_b128 v[196:199], v174 offset:37888
	ds_read_b128 v[200:203], v174 offset:38912
	ds_read_b128 v[204:207], v174 offset:39936
	global_load_lds_dwordx4 v[216:217], off
	v_lshl_add_u64 v[216:217], s[38:39], 0, v[148:149]
	s_mov_b32 m0, s84
	s_nop 0
	global_load_lds_dwordx4 v[216:217], off
	s_waitcnt vmcnt(8)
	s_waitcnt lgkmcnt(0)
	s_barrier
; #define PG8_STAGE(bufoff, gbase, voff) do { _Pragma("unroll") for (int _i = 0; _i < 2; ++_i) \
;         __builtin_amdgcn_global_load_lds((const unsigned*)((const char*)(gbase) + (voff)[_i]), (LAS unsigned*)(lds + (bufoff) + ldsw + _i * 8192), 16, 0, 0); } while (0)
; #define PG8_LDA(dst, b, h) do { _Pragma("unroll") for (int m = 0; m < 4; ++m) _Pragma("unroll") for (int k = 0; k < 2; ++k) dst[m][k] = *(const LAS bf16x8*)(lds + PG8_SA(b, h) + aoff + m * 2048 + k * 1024); } while (0)
; #define PG8_MMA(ai, bj, At, Bt) do { __builtin_amdgcn_s_setprio(1); _Pragma("unroll") for (int m = 0; m < 4; ++m) _Pragma("unroll") for (int n = 0; n < 2; ++n) _Pragma("unroll") for (int k = 0; k < 2; ++k) \
;         acc[ai][bj][m][n] = __builtin_amdgcn_mfma_f32_16x16x32_bf16(Bt[n][k], At[m][k], acc[ai][bj][m][n], 0, 0, 0); __builtin_amdgcn_s_setprio(0); } while (0)
; #define PG8_WAIT_V(n) asm volatile("s_waitcnt vmcnt(" #n ")" ::: "memory")
; #define PG8_WAIT_L(n) asm volatile("s_waitcnt lgkmcnt(" #n ")" ::: "memory")
; #define PG8_BAR __builtin_amdgcn_s_barrier()
; #define PG8_SCHED __builtin_amdgcn_sched_barrier(0)
; template <class Epi, class Sched, bool ALIGN_EPI>
; __device__ __forceinline__ void gemm_phase(LAS unsigned char* lds, const Gemm g, const Sched& S, const Epi& E, int wave_s) {
;     ...
;             PG8_WAIT_V(8); PG8_WAIT_L(0); PG8_BAR; PG8_MMA(0, 0, At, B0); PG8_MMA(0, 1, At, B1); PG8_BAR; PG8_SCHED;
;             PG8_LDA(At, 1, 1); PG8_STAGE(PG8_SB(1, 0), b3, voffB); PG8_STAGE(PG8_SB(1, 1), b3 + hstepB, voffB); PG8_STAGE(PG8_SA(1, 0), a3, voffA);
;             PG8_WAIT_V(8); PG8_WAIT_L(0); PG8_BAR; PG8_MMA(1, 0, At, B0); PG8_MMA(1, 1, At, B1); PG8_BAR; PG8_SCHED;
;         }
;         if constexpr (ALIGN_EPI) { if (wr == 0) PG8_BAR; }
	s_setprio 1
	s_waitcnt lgkmcnt(0)
	v_mfma_f32_16x16x32_bf16 v[126:129], v[130:133], v[176:179], v[126:129]
	v_mfma_f32_16x16x32_bf16 v[122:125], v[138:141], v[176:179], v[122:125]
	v_mfma_f32_16x16x32_bf16 v[110:113], v[130:133], v[184:187], v[110:113]
	v_mfma_f32_16x16x32_bf16 v[106:109], v[138:141], v[184:187], v[106:109]
	v_mfma_f32_16x16x32_bf16 v[94:97], v[130:133], v[192:195], v[94:97]
	v_mfma_f32_16x16x32_bf16 v[90:93], v[138:141], v[192:195], v[90:93]
	v_mfma_f32_16x16x32_bf16 v[78:81], v[130:133], v[200:203], v[78:81]
	v_mfma_f32_16x16x32_bf16 v[74:77], v[138:141], v[200:203], v[74:77]
	v_mfma_f32_16x16x32_bf16 v[126:129], v[134:137], v[180:183], v[126:129]
	v_mfma_f32_16x16x32_bf16 v[122:125], v[142:145], v[180:183], v[122:125]
	v_mfma_f32_16x16x32_bf16 v[110:113], v[134:137], v[188:191], v[110:113]
	v_mfma_f32_16x16x32_bf16 v[106:109], v[142:145], v[188:191], v[106:109]
	v_mfma_f32_16x16x32_bf16 v[94:97], v[134:137], v[196:199], v[94:97]
	v_mfma_f32_16x16x32_bf16 v[90:93], v[142:145], v[196:199], v[90:93]
	v_mfma_f32_16x16x32_bf16 v[78:81], v[134:137], v[204:207], v[78:81]
	v_mfma_f32_16x16x32_bf16 v[74:77], v[142:145], v[204:207], v[74:77]
	s_setprio 0
	s_setprio 1
	v_mfma_f32_16x16x32_bf16 v[118:121], v[158:161], v[176:179], v[118:121]
	v_mfma_f32_16x16x32_bf16 v[114:117], v[166:169], v[176:179], v[114:117]
	v_mfma_f32_16x16x32_bf16 v[102:105], v[158:161], v[184:187], v[102:105]
	v_mfma_f32_16x16x32_bf16 v[98:101], v[166:169], v[184:187], v[98:101]
	v_mfma_f32_16x16x32_bf16 v[86:89], v[158:161], v[192:195], v[86:89]
	v_mfma_f32_16x16x32_bf16 v[82:85], v[166:169], v[192:195], v[82:85]
	v_mfma_f32_16x16x32_bf16 v[70:73], v[158:161], v[200:203], v[70:73]
	v_mfma_f32_16x16x32_bf16 v[66:69], v[166:169], v[200:203], v[66:69]
	v_mfma_f32_16x16x32_bf16 v[118:121], v[162:165], v[180:183], v[118:121]
	v_mfma_f32_16x16x32_bf16 v[114:117], v[170:173], v[180:183], v[114:117]
	v_mfma_f32_16x16x32_bf16 v[102:105], v[162:165], v[188:191], v[102:105]
	v_mfma_f32_16x16x32_bf16 v[98:101], v[170:173], v[188:191], v[98:101]
	v_mfma_f32_16x16x32_bf16 v[86:89], v[162:165], v[196:199], v[86:89]
	v_mfma_f32_16x16x32_bf16 v[82:85], v[170:173], v[196:199], v[82:85]
	v_mfma_f32_16x16x32_bf16 v[70:73], v[162:165], v[204:207], v[70:73]
	v_mfma_f32_16x16x32_bf16 v[66:69], v[170:173], v[204:207], v[66:69]
	s_setprio 0
	s_barrier
	s_add_i32 s4, s4, s43
	v_lshl_add_u64 v[208:209], v[208:209], 0, s[74:75]
	s_mov_b32 m0, s4
	ds_read_b128 v[176:179], v174 offset:49152
	ds_read_b128 v[180:183], v174 offset:50176
	ds_read_b128 v[184:187], v174 offset:51200
	ds_read_b128 v[188:191], v174 offset:52224
	ds_read_b128 v[192:195], v174 offset:53248
	ds_read_b128 v[196:199], v174 offset:54272
	ds_read_b128 v[200:203], v174 offset:55296
	ds_read_b128 v[204:207], v174 offset:56320
	global_load_lds_dwordx4 v[208:209], off
	s_add_i32 m0, s4, 0x2000
	s_add_u32 s36, s36, 0x40080
	v_lshl_add_u64 v[208:209], v[210:211], 0, s[74:75]
	s_addc_u32 s37, s37, 0
	s_add_i32 s4, s5, s43
	global_load_lds_dwordx4 v[208:209], off
	v_lshl_add_u64 v[208:209], s[36:37], 0, v[150:151]
	s_mov_b32 m0, s4
	s_nop 0
	global_load_lds_dwordx4 v[208:209], off
	v_lshl_add_u64 v[208:209], s[36:37], 0, v[146:147]
	s_add_i32 m0, s4, 0x2000
	s_nop 0
	global_load_lds_dwordx4 v[208:209], off
	v_lshl_add_u64 v[208:209], v[212:213], 0, s[74:75]
	s_mov_b32 m0, s88
	s_nop 0
	global_load_lds_dwordx4 v[208:209], off
	v_lshl_add_u64 v[208:209], v[214:215], 0, s[74:75]
	s_mov_b32 m0, s89
	s_nop 0
	global_load_lds_dwordx4 v[208:209], off
	s_waitcnt vmcnt(8)
	s_waitcnt lgkmcnt(0)
	s_barrier
	s_setprio 1
	s_waitcnt lgkmcnt(0)
	v_mfma_f32_16x16x32_bf16 v[62:65], v[130:133], v[176:179], v[62:65]
	v_mfma_f32_16x16x32_bf16 v[58:61], v[138:141], v[176:179], v[58:61]
	v_mfma_f32_16x16x32_bf16 v[46:49], v[130:133], v[184:187], v[46:49]
	v_mfma_f32_16x16x32_bf16 v[42:45], v[138:141], v[184:187], v[42:45]
	v_mfma_f32_16x16x32_bf16 v[30:33], v[130:133], v[192:195], v[30:33]
	v_mfma_f32_16x16x32_bf16 v[26:29], v[138:141], v[192:195], v[26:29]
	v_mfma_f32_16x16x32_bf16 v[14:17], v[130:133], v[200:203], v[14:17]
	v_mfma_f32_16x16x32_bf16 v[10:13], v[138:141], v[200:203], v[10:13]
	v_mfma_f32_16x16x32_bf16 v[62:65], v[134:137], v[180:183], v[62:65]
	v_mfma_f32_16x16x32_bf16 v[58:61], v[142:145], v[180:183], v[58:61]
	v_mfma_f32_16x16x32_bf16 v[46:49], v[134:137], v[188:191], v[46:49]
	v_mfma_f32_16x16x32_bf16 v[42:45], v[142:145], v[188:191], v[42:45]
	v_mfma_f32_16x16x32_bf16 v[30:33], v[134:137], v[196:199], v[30:33]
	v_mfma_f32_16x16x32_bf16 v[26:29], v[142:145], v[196:199], v[26:29]
	v_mfma_f32_16x16x32_bf16 v[14:17], v[134:137], v[204:207], v[14:17]
	v_mfma_f32_16x16x32_bf16 v[10:13], v[142:145], v[204:207], v[10:13]
	s_setprio 0
	s_setprio 1
	v_mfma_f32_16x16x32_bf16 v[54:57], v[158:161], v[176:179], v[54:57]
	v_mfma_f32_16x16x32_bf16 v[50:53], v[166:169], v[176:179], v[50:53]
	v_mfma_f32_16x16x32_bf16 v[38:41], v[158:161], v[184:187], v[38:41]
	v_mfma_f32_16x16x32_bf16 v[34:37], v[166:169], v[184:187], v[34:37]
	v_mfma_f32_16x16x32_bf16 v[22:25], v[158:161], v[192:195], v[22:25]
	v_mfma_f32_16x16x32_bf16 v[18:21], v[166:169], v[192:195], v[18:21]
	v_mfma_f32_16x16x32_bf16 v[6:9], v[158:161], v[200:203], v[6:9]
	v_mfma_f32_16x16x32_bf16 v[2:5], v[166:169], v[200:203], v[2:5]
	v_mfma_f32_16x16x32_bf16 v[54:57], v[162:165], v[180:183], v[54:57]
	v_mfma_f32_16x16x32_bf16 v[50:53], v[170:173], v[180:183], v[50:53]
	v_mfma_f32_16x16x32_bf16 v[38:41], v[162:165], v[188:191], v[38:41]
	v_mfma_f32_16x16x32_bf16 v[34:37], v[170:173], v[188:191], v[34:37]
	v_mfma_f32_16x16x32_bf16 v[22:25], v[162:165], v[196:199], v[22:25]
	v_mfma_f32_16x16x32_bf16 v[18:21], v[170:173], v[196:199], v[18:21]
	v_mfma_f32_16x16x32_bf16 v[6:9], v[162:165], v[204:207], v[6:9]
	v_mfma_f32_16x16x32_bf16 v[2:5], v[170:173], v[204:207], v[2:5]
	s_setprio 0
	s_barrier
	s_add_i32 s94, s94, 2
	s_add_u32 s34, s34, 0x100
	s_addc_u32 s35, s35, 0
	s_add_u32 s92, s92, 0x100
	s_addc_u32 s93, s93, 0
	s_cmp_gt_u32 s94, 13
	s_cbranch_scc0 .LBB0_1490
	s_and_b64 vcc, exec, s[78:79]
	s_cbranch_vccz .LBB0_1493
	s_barrier

; #define PG8_STAGE(bufoff, gbase, voff) do { _Pragma("unroll") for (int _i = 0; _i < 2; ++_i) \
;         __builtin_amdgcn_global_load_lds((const unsigned*)((const char*)(gbase) + (voff)[_i]), (LAS unsigned*)(lds + (bufoff) + ldsw + _i * 8192), 16, 0, 0); } while (0)
; #define PG8_LDA(dst, b, h) do { _Pragma("unroll") for (int m = 0; m < 4; ++m) _Pragma("unroll") for (int k = 0; k < 2; ++k) dst[m][k] = *(const LAS bf16x8*)(lds + PG8_SA(b, h) + aoff + m * 2048 + k * 1024); } while (0)
; #define PG8_LDB(dst, b, h) do { _Pragma("unroll") for (int n = 0; n < 2; ++n) _Pragma("unroll") for (int k = 0; k < 2; ++k) dst[n][k] = *(const LAS bf16x8*)(lds + PG8_SB(b, h) + boff + n * 2048 + k * 1024); } while (0)
; #define PG8_MMA(ai, bj, At, Bt) do { __builtin_amdgcn_s_setprio(1); _Pragma("unroll") for (int m = 0; m < 4; ++m) _Pragma("unroll") for (int n = 0; n < 2; ++n) _Pragma("unroll") for (int k = 0; k < 2; ++k) \
;         acc[ai][bj][m][n] = __builtin_amdgcn_mfma_f32_16x16x32_bf16(Bt[n][k], At[m][k], acc[ai][bj][m][n], 0, 0, 0); __builtin_amdgcn_s_setprio(0); } while (0)
; #define PG8_WAIT_V(n) asm volatile("s_waitcnt vmcnt(" #n ")" ::: "memory")
; #define PG8_WAIT_L(n) asm volatile("s_waitcnt lgkmcnt(" #n ")" ::: "memory")
; #define PG8_BAR __builtin_amdgcn_s_barrier()
; template <class Epi, class Sched, bool ALIGN_EPI>
; __device__ __forceinline__ void gemm_phase(LAS unsigned char* lds, const Gemm g, const Sched& S, const Epi& E, int wave_s) {
;     ...
;         for (int t = 0; t < nt; t += 2) {
;             const bool last = (t == nt - 2);
;             const char* a1 = cA + (size_t)(t + 1) * kstep;
;             const char* a2 = last ? nA : cA + (size_t)(t + 2) * kstep; const char* b2 = last ? nB : cB + (size_t)(t + 2) * kstep;
;             const char* a3 = a2 + kstep; const char* b3 = b2 + kstep;
;             PG8_LDB(B0, 0, 0); PG8_LDB(B1, 0, 1); PG8_SCHED; PG8_LDA(At, 0, 0); PG8_STAGE(PG8_SA(1, 1), a1 + hstepA, voffA);
;             PG8_WAIT_V(8); PG8_WAIT_L(0); PG8_BAR; PG8_MMA(0, 0, At, B0); PG8_MMA(0, 1, At, B1); PG8_BAR; PG8_SCHED;
;     ...
; #pragma unroll
;         for (int a = 0; a < 2; ++a)
; #pragma unroll
;             for (int b = 0; b < 2; ++b)
; #pragma unroll
;                 for (int m = 0; m < 4; ++m)
; #pragma unroll
;                     for (int n = 0; n < 2; ++n) acc[a][b][m][n] = (f32x4){0.f, 0.f, 0.f, 0.f};
.LBB0_1556:
	s_add_u32 s30, s10, 0xfff00080
	s_addc_u32 s31, s11, -1
	s_add_i32 s95, 0, 0x10000
	s_cmp_eq_u32 s94, 60
	s_cselect_b32 s35, s25, s31
	s_cselect_b32 s34, s90, s30
	s_cselect_b32 s31, s23, s93
	s_cselect_b32 s30, s91, s92
	s_add_i32 s6, 0, 0x14000
	v_add_u32_e32 v78, s95, v1
	v_add_u32_e32 v170, s6, v1
	ds_read_b128 v[66:69], v78
	ds_read_b128 v[70:73], v78 offset:1024
	ds_read_b128 v[74:77], v78 offset:2048
	ds_read_b128 v[78:81], v78 offset:3072
	ds_read_b128 v[146:149], v170
	ds_read_b128 v[150:153], v170 offset:1024
	ds_read_b128 v[154:157], v170 offset:2048
	ds_read_b128 v[170:173], v170 offset:3072
	v_lshl_add_u64 v[208:209], s[10:11], 0, v[166:167]
	s_add_i32 m0, s39, 0xc000
	ds_read_b128 v[174:177], v198
	ds_read_b128 v[178:181], v198 offset:1024
	ds_read_b128 v[182:185], v198 offset:2048
	ds_read_b128 v[186:189], v198 offset:3072
	ds_read_b128 v[190:193], v198 offset:4096
	ds_read_b128 v[194:197], v198 offset:5120
	ds_read_b128 v[200:203], v198 offset:6144
	ds_read_b128 v[204:207], v198 offset:7168
	global_load_lds_dwordx4 v[208:209], off
	v_lshl_add_u64 v[208:209], s[10:11], 0, v[168:169]
	s_add_i32 m0, s39, 0xe000
	s_nop 0
	global_load_lds_dwordx4 v[208:209], off
	s_cmp_lg_u32 s94, -2
	s_cbranch_scc1 .Lzacc_1556_skip
	v_mov_b32_e32 v3, 0
	v_mov_b32_e32 v4, 0
	v_mov_b32_e32 v5, 0
	v_mov_b32_e32 v6, 0
	v_mov_b32_e32 v7, 0
	v_mov_b32_e32 v8, 0
	v_mov_b32_e32 v9, 0
	v_mov_b32_e32 v18, 0
	v_mov_b32_e32 v19, 0
	v_mov_b32_e32 v20, 0
	v_mov_b32_e32 v21, 0
	v_mov_b32_e32 v22, 0
	v_mov_b32_e32 v23, 0
	v_mov_b32_e32 v24, 0
	v_mov_b32_e32 v25, 0
	v_mov_b32_e32 v34, 0
	v_mov_b32_e32 v35, 0
	v_mov_b32_e32 v36, 0
	v_mov_b32_e32 v37, 0
	v_mov_b32_e32 v38, 0
	v_mov_b32_e32 v39, 0
	v_mov_b32_e32 v40, 0
	v_mov_b32_e32 v41, 0
	v_mov_b32_e32 v50, 0
	v_mov_b32_e32 v51, 0
	v_mov_b32_e32 v52, 0
	v_mov_b32_e32 v53, 0
	v_mov_b32_e32 v54, 0
	v_mov_b32_e32 v55, 0
	v_mov_b32_e32 v56, 0
	v_mov_b32_e32 v57, 0
	v_mov_b32_e32 v10, 0
	v_mov_b32_e32 v11, 0
	v_mov_b32_e32 v12, 0
	v_mov_b32_e32 v13, 0
	v_mov_b32_e32 v14, 0
	v_mov_b32_e32 v15, 0
	v_mov_b32_e32 v16, 0
	v_mov_b32_e32 v17, 0
	v_mov_b32_e32 v26, 0
	v_mov_b32_e32 v27, 0
	v_mov_b32_e32 v28, 0
	v_mov_b32_e32 v29, 0
	v_mov_b32_e32 v30, 0
	v_mov_b32_e32 v31, 0
	v_mov_b32_e32 v32, 0
	v_mov_b32_e32 v33, 0
	v_mov_b32_e32 v42, 0
	v_mov_b32_e32 v43, 0
	v_mov_b32_e32 v44, 0
	v_mov_b32_e32 v45, 0
	v_mov_b32_e32 v46, 0
	v_mov_b32_e32 v47, 0
	v_mov_b32_e32 v48, 0
	v_mov_b32_e32 v49, 0
	v_mov_b32_e32 v58, 0
	v_mov_b32_e32 v59, 0
	v_mov_b32_e32 v60, 0
	v_mov_b32_e32 v61, 0
	v_mov_b32_e32 v62, 0
	v_mov_b32_e32 v63, 0
	v_mov_b32_e32 v64, 0
	v_mov_b32_e32 v65, 0
	v_mov_b32_e32 v82, 0
	v_mov_b32_e32 v83, 0
	v_mov_b32_e32 v84, 0
	v_mov_b32_e32 v85, 0
	v_mov_b32_e32 v86, 0
	v_mov_b32_e32 v87, 0
	v_mov_b32_e32 v88, 0
	v_mov_b32_e32 v89, 0
	v_mov_b32_e32 v98, 0
	v_mov_b32_e32 v99, 0
	v_mov_b32_e32 v100, 0
	v_mov_b32_e32 v101, 0
	v_mov_b32_e32 v102, 0
	v_mov_b32_e32 v103, 0
	v_mov_b32_e32 v104, 0
	v_mov_b32_e32 v105, 0
	v_mov_b32_e32 v114, 0
	v_mov_b32_e32 v115, 0
	v_mov_b32_e32 v116, 0
	v_mov_b32_e32 v117, 0
	v_mov_b32_e32 v118, 0
	v_mov_b32_e32 v119, 0
	v_mov_b32_e32 v120, 0
	v_mov_b32_e32 v121, 0
	v_mov_b32_e32 v130, 0
	v_mov_b32_e32 v131, 0
	v_mov_b32_e32 v132, 0
	v_mov_b32_e32 v133, 0
	v_mov_b32_e32 v134, 0
	v_mov_b32_e32 v135, 0
	v_mov_b32_e32 v136, 0
	v_mov_b32_e32 v137, 0
	v_mov_b32_e32 v90, 0
	v_mov_b32_e32 v91, 0
	v_mov_b32_e32 v92, 0
	v_mov_b32_e32 v93, 0
	v_mov_b32_e32 v94, 0
	v_mov_b32_e32 v95, 0
	v_mov_b32_e32 v96, 0
	v_mov_b32_e32 v97, 0
	v_mov_b32_e32 v106, 0
	v_mov_b32_e32 v107, 0
	v_mov_b32_e32 v108, 0
	v_mov_b32_e32 v109, 0
	v_mov_b32_e32 v110, 0
	v_mov_b32_e32 v111, 0
	v_mov_b32_e32 v112, 0
	v_mov_b32_e32 v113, 0
	v_mov_b32_e32 v122, 0
	v_mov_b32_e32 v123, 0
	v_mov_b32_e32 v124, 0
	v_mov_b32_e32 v125, 0
	v_mov_b32_e32 v126, 0
	v_mov_b32_e32 v127, 0
	v_mov_b32_e32 v128, 0
	v_mov_b32_e32 v129, 0
	v_mov_b32_e32 v138, 0
	v_mov_b32_e32 v139, 0
	v_mov_b32_e32 v140, 0
	v_mov_b32_e32 v141, 0
	v_mov_b32_e32 v142, 0
	v_mov_b32_e32 v143, 0
	v_mov_b32_e32 v144, 0
	v_mov_b32_e32 v145, 0
.Lzacc_1556_skip:
	s_waitcnt vmcnt(8)
	s_waitcnt lgkmcnt(0)
	s_barrier
	s_setprio 1
	s_waitcnt lgkmcnt(0)
	v_mfma_f32_16x16x32_bf16 v[142:145], v[66:69], v[174:177], v[142:145]
	v_mfma_f32_16x16x32_bf16 v[138:141], v[74:77], v[174:177], v[138:141]
	v_mfma_f32_16x16x32_bf16 v[126:129], v[66:69], v[182:185], v[126:129]
	v_mfma_f32_16x16x32_bf16 v[122:125], v[74:77], v[182:185], v[122:125]
	v_mfma_f32_16x16x32_bf16 v[110:113], v[66:69], v[190:193], v[110:113]
	v_mfma_f32_16x16x32_bf16 v[106:109], v[74:77], v[190:193], v[106:109]
	v_mfma_f32_16x16x32_bf16 v[94:97], v[66:69], v[200:203], v[94:97]
	v_mfma_f32_16x16x32_bf16 v[90:93], v[74:77], v[200:203], v[90:93]
	v_mfma_f32_16x16x32_bf16 v[142:145], v[70:73], v[178:181], v[142:145]
	v_mfma_f32_16x16x32_bf16 v[138:141], v[78:81], v[178:181], v[138:141]
	v_mfma_f32_16x16x32_bf16 v[126:129], v[70:73], v[186:189], v[126:129]
	v_mfma_f32_16x16x32_bf16 v[122:125], v[78:81], v[186:189], v[122:125]
	v_mfma_f32_16x16x32_bf16 v[110:113], v[70:73], v[194:197], v[110:113]
	v_mfma_f32_16x16x32_bf16 v[106:109], v[78:81], v[194:197], v[106:109]
	v_mfma_f32_16x16x32_bf16 v[94:97], v[70:73], v[204:207], v[94:97]
	v_mfma_f32_16x16x32_bf16 v[90:93], v[78:81], v[204:207], v[90:93]
	s_setprio 0
	s_setprio 1
	v_mfma_f32_16x16x32_bf16 v[134:137], v[146:149], v[174:177], v[134:137]
	v_mfma_f32_16x16x32_bf16 v[130:133], v[154:157], v[174:177], v[130:133]
	v_mfma_f32_16x16x32_bf16 v[118:121], v[146:149], v[182:185], v[118:121]
	v_mfma_f32_16x16x32_bf16 v[114:117], v[154:157], v[182:185], v[114:117]
	v_mfma_f32_16x16x32_bf16 v[102:105], v[146:149], v[190:193], v[102:105]
	v_mfma_f32_16x16x32_bf16 v[98:101], v[154:157], v[190:193], v[98:101]
	v_mfma_f32_16x16x32_bf16 v[86:89], v[146:149], v[200:203], v[86:89]
	v_mfma_f32_16x16x32_bf16 v[82:85], v[154:157], v[200:203], v[82:85]
	v_mfma_f32_16x16x32_bf16 v[134:137], v[150:153], v[178:181], v[134:137]
	v_mfma_f32_16x16x32_bf16 v[130:133], v[170:173], v[178:181], v[130:133]
	v_mfma_f32_16x16x32_bf16 v[118:121], v[150:153], v[186:189], v[118:121]
	v_mfma_f32_16x16x32_bf16 v[114:117], v[170:173], v[186:189], v[114:117]
	v_mfma_f32_16x16x32_bf16 v[102:105], v[150:153], v[194:197], v[102:105]
	v_mfma_f32_16x16x32_bf16 v[98:101], v[170:173], v[194:197], v[98:101]
	v_mfma_f32_16x16x32_bf16 v[86:89], v[150:153], v[204:207], v[86:89]
	v_mfma_f32_16x16x32_bf16 v[82:85], v[170:173], v[204:207], v[82:85]
	s_setprio 0
	s_barrier
; #define PG8_STAGE(bufoff, gbase, voff) do { _Pragma("unroll") for (int _i = 0; _i < 2; ++_i) \
;         __builtin_amdgcn_global_load_lds((const unsigned*)((const char*)(gbase) + (voff)[_i]), (LAS unsigned*)(lds + (bufoff) + ldsw + _i * 8192), 16, 0, 0); } while (0)
; #define PG8_LDA(dst, b, h) do { _Pragma("unroll") for (int m = 0; m < 4; ++m) _Pragma("unroll") for (int k = 0; k < 2; ++k) dst[m][k] = *(const LAS bf16x8*)(lds + PG8_SA(b, h) + aoff + m * 2048 + k * 1024); } while (0)
; #define PG8_LDB(dst, b, h) do { _Pragma("unroll") for (int n = 0; n < 2; ++n) _Pragma("unroll") for (int k = 0; k < 2; ++k) dst[n][k] = *(const LAS bf16x8*)(lds + PG8_SB(b, h) + boff + n * 2048 + k * 1024); } while (0)
; #define PG8_MMA(ai, bj, At, Bt) do { __builtin_amdgcn_s_setprio(1); _Pragma("unroll") for (int m = 0; m < 4; ++m) _Pragma("unroll") for (int n = 0; n < 2; ++n) _Pragma("unroll") for (int k = 0; k < 2; ++k) \
;         acc[ai][bj][m][n] = __builtin_amdgcn_mfma_f32_16x16x32_bf16(Bt[n][k], At[m][k], acc[ai][bj][m][n], 0, 0, 0); __builtin_amdgcn_s_setprio(0); } while (0)
; #define PG8_WAIT_V(n) asm volatile("s_waitcnt vmcnt(" #n ")" ::: "memory")
; #define PG8_WAIT_L(n) asm volatile("s_waitcnt lgkmcnt(" #n ")" ::: "memory")
; #define PG8_BAR __builtin_amdgcn_s_barrier()
; #define PG8_SCHED __builtin_amdgcn_sched_barrier(0)
; template <class Epi, class Sched, bool ALIGN_EPI>
; __device__ __forceinline__ void gemm_phase(LAS unsigned char* lds, const Gemm g, const Sched& S, const Epi& E, int wave_s) {
;     ...
;             PG8_LDA(At, 0, 1); PG8_STAGE(PG8_SB(0, 0), b2, voffB); PG8_STAGE(PG8_SB(0, 1), b2 + hstepB, voffB); PG8_STAGE(PG8_SA(0, 0), a2, voffA);
;             PG8_WAIT_V(8); PG8_WAIT_L(0); PG8_BAR; PG8_MMA(1, 0, At, B0); PG8_MMA(1, 1, At, B1); PG8_BAR; PG8_SCHED;
;             PG8_LDB(B0, 1, 0); PG8_LDB(B1, 1, 1); PG8_SCHED; PG8_LDA(At, 1, 0); PG8_STAGE(PG8_SA(0, 1), a2 + hstepA, voffA);
;             PG8_WAIT_V(8); PG8_WAIT_L(0); PG8_BAR; PG8_MMA(0, 0, At, B0); PG8_MMA(0, 1, At, B1); PG8_BAR; PG8_SCHED;
	s_add_i32 s7, s95, s38
	v_lshl_add_u64 v[208:209], s[30:31], 0, v[162:163]
	s_mov_b32 m0, s7
	ds_read_b128 v[174:177], v198 offset:16384
	ds_read_b128 v[178:181], v198 offset:17408
	ds_read_b128 v[182:185], v198 offset:18432
	ds_read_b128 v[186:189], v198 offset:19456
	ds_read_b128 v[190:193], v198 offset:20480
	ds_read_b128 v[194:197], v198 offset:21504
	ds_read_b128 v[200:203], v198 offset:22528
	ds_read_b128 v[204:207], v198 offset:23552
	global_load_lds_dwordx4 v[208:209], off
	s_add_i32 m0, s7, 0x2000
	s_add_u32 vcc_lo, s30, 0x100000
	v_lshl_add_u64 v[210:211], s[30:31], 0, v[158:159]
	s_addc_u32 vcc_hi, s31, 0
	s_add_i32 s6, s6, s38
	global_load_lds_dwordx4 v[210:211], off
	v_lshl_add_u64 v[212:213], vcc, 0, v[162:163]
	s_mov_b32 m0, s6
	v_lshl_add_u64 v[214:215], s[34:35], 0, v[160:161]
	global_load_lds_dwordx4 v[212:213], off
	v_lshl_add_u64 v[212:213], vcc, 0, v[158:159]
	s_add_i32 m0, s6, 0x2000
	s_nop 0
	global_load_lds_dwordx4 v[212:213], off
	v_lshl_add_u64 v[212:213], s[34:35], 0, v[164:165]
	s_mov_b32 m0, s39
	s_nop 0
	global_load_lds_dwordx4 v[212:213], off
	s_mov_b32 m0, s46
	s_nop 0
	global_load_lds_dwordx4 v[214:215], off
	s_waitcnt vmcnt(8)
	s_waitcnt lgkmcnt(0)
	s_barrier
	s_setprio 1
	s_waitcnt lgkmcnt(0)
	v_mfma_f32_16x16x32_bf16 v[62:65], v[66:69], v[174:177], v[62:65]
	v_mfma_f32_16x16x32_bf16 v[58:61], v[74:77], v[174:177], v[58:61]
	v_mfma_f32_16x16x32_bf16 v[46:49], v[66:69], v[182:185], v[46:49]
	v_mfma_f32_16x16x32_bf16 v[42:45], v[74:77], v[182:185], v[42:45]
	v_mfma_f32_16x16x32_bf16 v[30:33], v[66:69], v[190:193], v[30:33]
	v_mfma_f32_16x16x32_bf16 v[26:29], v[74:77], v[190:193], v[26:29]
	v_mfma_f32_16x16x32_bf16 v[14:17], v[66:69], v[200:203], v[14:17]
	v_mfma_f32_16x16x32_bf16 v[10:13], v[74:77], v[200:203], v[10:13]
	v_mfma_f32_16x16x32_bf16 v[62:65], v[70:73], v[178:181], v[62:65]
	v_mfma_f32_16x16x32_bf16 v[58:61], v[78:81], v[178:181], v[58:61]
	v_mfma_f32_16x16x32_bf16 v[46:49], v[70:73], v[186:189], v[46:49]
	v_mfma_f32_16x16x32_bf16 v[42:45], v[78:81], v[186:189], v[42:45]
	v_mfma_f32_16x16x32_bf16 v[30:33], v[70:73], v[194:197], v[30:33]
	v_mfma_f32_16x16x32_bf16 v[26:29], v[78:81], v[194:197], v[26:29]
	v_mfma_f32_16x16x32_bf16 v[14:17], v[70:73], v[204:207], v[14:17]
	v_mfma_f32_16x16x32_bf16 v[10:13], v[78:81], v[204:207], v[10:13]
	s_setprio 0
	s_setprio 1
	v_mfma_f32_16x16x32_bf16 v[54:57], v[146:149], v[174:177], v[54:57]
	v_mfma_f32_16x16x32_bf16 v[50:53], v[154:157], v[174:177], v[50:53]
	v_mfma_f32_16x16x32_bf16 v[38:41], v[146:149], v[182:185], v[38:41]
	v_mfma_f32_16x16x32_bf16 v[34:37], v[154:157], v[182:185], v[34:37]
	v_mfma_f32_16x16x32_bf16 v[22:25], v[146:149], v[190:193], v[22:25]
	v_mfma_f32_16x16x32_bf16 v[18:21], v[154:157], v[190:193], v[18:21]
	v_mfma_f32_16x16x32_bf16 v[6:9], v[146:149], v[200:203], v[6:9]
	v_mfma_f32_16x16x32_bf16 v[2:5], v[154:157], v[200:203], v[2:5]
	v_mfma_f32_16x16x32_bf16 v[54:57], v[150:153], v[178:181], v[54:57]
	v_mfma_f32_16x16x32_bf16 v[50:53], v[170:173], v[178:181], v[50:53]
	v_mfma_f32_16x16x32_bf16 v[38:41], v[150:153], v[186:189], v[38:41]
	v_mfma_f32_16x16x32_bf16 v[34:37], v[170:173], v[186:189], v[34:37]
	v_mfma_f32_16x16x32_bf16 v[22:25], v[150:153], v[194:197], v[22:25]
	v_mfma_f32_16x16x32_bf16 v[18:21], v[170:173], v[194:197], v[18:21]
	v_mfma_f32_16x16x32_bf16 v[6:9], v[150:153], v[204:207], v[6:9]
	v_mfma_f32_16x16x32_bf16 v[2:5], v[170:173], v[204:207], v[2:5]
	s_setprio 0
	s_barrier
	s_add_i32 s6, 0, 0x18000
	s_add_i32 s7, 0, 0x1c000
	v_add_u32_e32 v78, s6, v1
	v_add_u32_e32 v170, s7, v1
	ds_read_b128 v[66:69], v78
	ds_read_b128 v[70:73], v78 offset:1024
	ds_read_b128 v[74:77], v78 offset:2048
	ds_read_b128 v[78:81], v78 offset:3072
	ds_read_b128 v[146:149], v170
	ds_read_b128 v[150:153], v170 offset:1024
	ds_read_b128 v[154:157], v170 offset:2048
	ds_read_b128 v[170:173], v170 offset:3072
	s_add_u32 s34, s34, 0x100000
	s_addc_u32 s35, s35, 0
	s_mov_b32 m0, s47
	v_lshl_add_u64 v[216:217], s[34:35], 0, v[164:165]
	ds_read_b128 v[174:177], v198 offset:32768
	ds_read_b128 v[178:181], v198 offset:33792
	ds_read_b128 v[182:185], v198 offset:34816
	ds_read_b128 v[186:189], v198 offset:35840
	ds_read_b128 v[190:193], v198 offset:36864
	ds_read_b128 v[194:197], v198 offset:37888
	ds_read_b128 v[200:203], v198 offset:38912
	ds_read_b128 v[204:207], v198 offset:39936
	global_load_lds_dwordx4 v[216:217], off
	v_lshl_add_u64 v[216:217], s[34:35], 0, v[160:161]
	s_mov_b32 m0, s48
	s_nop 0
	global_load_lds_dwordx4 v[216:217], off
	s_waitcnt vmcnt(8)
	s_waitcnt lgkmcnt(0)
	s_barrier
; #define PG8_STAGE(bufoff, gbase, voff) do { _Pragma("unroll") for (int _i = 0; _i < 2; ++_i) \
;         __builtin_amdgcn_global_load_lds((const unsigned*)((const char*)(gbase) + (voff)[_i]), (LAS unsigned*)(lds + (bufoff) + ldsw + _i * 8192), 16, 0, 0); } while (0)
; #define PG8_LDA(dst, b, h) do { _Pragma("unroll") for (int m = 0; m < 4; ++m) _Pragma("unroll") for (int k = 0; k < 2; ++k) dst[m][k] = *(const LAS bf16x8*)(lds + PG8_SA(b, h) + aoff + m * 2048 + k * 1024); } while (0)
; #define PG8_MMA(ai, bj, At, Bt) do { __builtin_amdgcn_s_setprio(1); _Pragma("unroll") for (int m = 0; m < 4; ++m) _Pragma("unroll") for (int n = 0; n < 2; ++n) _Pragma("unroll") for (int k = 0; k < 2; ++k) \
;         acc[ai][bj][m][n] = __builtin_amdgcn_mfma_f32_16x16x32_bf16(Bt[n][k], At[m][k], acc[ai][bj][m][n], 0, 0, 0); __builtin_amdgcn_s_setprio(0); } while (0)
; #define PG8_WAIT_V(n) asm volatile("s_waitcnt vmcnt(" #n ")" ::: "memory")
; #define PG8_WAIT_L(n) asm volatile("s_waitcnt lgkmcnt(" #n ")" ::: "memory")
; #define PG8_BAR __builtin_amdgcn_s_barrier()
; #define PG8_SCHED __builtin_amdgcn_sched_barrier(0)
; template <class Epi, class Sched, bool ALIGN_EPI>
; __device__ __forceinline__ void gemm_phase(LAS unsigned char* lds, const Gemm g, const Sched& S, const Epi& E, int wave_s) {
;     ...
;             PG8_WAIT_V(8); PG8_WAIT_L(0); PG8_BAR; PG8_MMA(0, 0, At, B0); PG8_MMA(0, 1, At, B1); PG8_BAR; PG8_SCHED;
;             PG8_LDA(At, 1, 1); PG8_STAGE(PG8_SB(1, 0), b3, voffB); PG8_STAGE(PG8_SB(1, 1), b3 + hstepB, voffB); PG8_STAGE(PG8_SA(1, 0), a3, voffA);
;             PG8_WAIT_V(8); PG8_WAIT_L(0); PG8_BAR; PG8_MMA(1, 0, At, B0); PG8_MMA(1, 1, At, B1); PG8_BAR; PG8_SCHED;
;         }
;         if constexpr (ALIGN_EPI) { if (wr == 0) PG8_BAR; }
	s_setprio 1
	s_waitcnt lgkmcnt(0)
	v_mfma_f32_16x16x32_bf16 v[142:145], v[66:69], v[174:177], v[142:145]
	v_mfma_f32_16x16x32_bf16 v[138:141], v[74:77], v[174:177], v[138:141]
	v_mfma_f32_16x16x32_bf16 v[126:129], v[66:69], v[182:185], v[126:129]
	v_mfma_f32_16x16x32_bf16 v[122:125], v[74:77], v[182:185], v[122:125]
	v_mfma_f32_16x16x32_bf16 v[110:113], v[66:69], v[190:193], v[110:113]
	v_mfma_f32_16x16x32_bf16 v[106:109], v[74:77], v[190:193], v[106:109]
	v_mfma_f32_16x16x32_bf16 v[94:97], v[66:69], v[200:203], v[94:97]
	v_mfma_f32_16x16x32_bf16 v[90:93], v[74:77], v[200:203], v[90:93]
	v_mfma_f32_16x16x32_bf16 v[142:145], v[70:73], v[178:181], v[142:145]
	v_mfma_f32_16x16x32_bf16 v[138:141], v[78:81], v[178:181], v[138:141]
	v_mfma_f32_16x16x32_bf16 v[126:129], v[70:73], v[186:189], v[126:129]
	v_mfma_f32_16x16x32_bf16 v[122:125], v[78:81], v[186:189], v[122:125]
	v_mfma_f32_16x16x32_bf16 v[110:113], v[70:73], v[194:197], v[110:113]
	v_mfma_f32_16x16x32_bf16 v[106:109], v[78:81], v[194:197], v[106:109]
	v_mfma_f32_16x16x32_bf16 v[94:97], v[70:73], v[204:207], v[94:97]
	v_mfma_f32_16x16x32_bf16 v[90:93], v[78:81], v[204:207], v[90:93]
	s_setprio 0
	s_setprio 1
	v_mfma_f32_16x16x32_bf16 v[134:137], v[146:149], v[174:177], v[134:137]
	v_mfma_f32_16x16x32_bf16 v[130:133], v[154:157], v[174:177], v[130:133]
	v_mfma_f32_16x16x32_bf16 v[118:121], v[146:149], v[182:185], v[118:121]
	v_mfma_f32_16x16x32_bf16 v[114:117], v[154:157], v[182:185], v[114:117]
	v_mfma_f32_16x16x32_bf16 v[102:105], v[146:149], v[190:193], v[102:105]
	v_mfma_f32_16x16x32_bf16 v[98:101], v[154:157], v[190:193], v[98:101]
	v_mfma_f32_16x16x32_bf16 v[86:89], v[146:149], v[200:203], v[86:89]
	v_mfma_f32_16x16x32_bf16 v[82:85], v[154:157], v[200:203], v[82:85]
	v_mfma_f32_16x16x32_bf16 v[134:137], v[150:153], v[178:181], v[134:137]
	v_mfma_f32_16x16x32_bf16 v[130:133], v[170:173], v[178:181], v[130:133]
	v_mfma_f32_16x16x32_bf16 v[118:121], v[150:153], v[186:189], v[118:121]
	v_mfma_f32_16x16x32_bf16 v[114:117], v[170:173], v[186:189], v[114:117]
	v_mfma_f32_16x16x32_bf16 v[102:105], v[150:153], v[194:197], v[102:105]
	v_mfma_f32_16x16x32_bf16 v[98:101], v[170:173], v[194:197], v[98:101]
	v_mfma_f32_16x16x32_bf16 v[86:89], v[150:153], v[204:207], v[86:89]
	v_mfma_f32_16x16x32_bf16 v[82:85], v[170:173], v[204:207], v[82:85]
	s_setprio 0
	s_barrier
	s_add_i32 s6, s6, s38
	v_lshl_add_u64 v[208:209], v[208:209], 0, s[74:75]
	s_mov_b32 m0, s6
	ds_read_b128 v[174:177], v198 offset:49152
	ds_read_b128 v[178:181], v198 offset:50176
	ds_read_b128 v[182:185], v198 offset:51200
	ds_read_b128 v[186:189], v198 offset:52224
	ds_read_b128 v[190:193], v198 offset:53248
	ds_read_b128 v[194:197], v198 offset:54272
	ds_read_b128 v[200:203], v198 offset:55296
	ds_read_b128 v[204:207], v198 offset:56320
	global_load_lds_dwordx4 v[208:209], off
	s_add_i32 m0, s6, 0x2000
	s_add_u32 s30, s30, 0x100080
	v_lshl_add_u64 v[208:209], v[210:211], 0, s[74:75]
	s_addc_u32 s31, s31, 0
	s_add_i32 s6, s7, s38
	global_load_lds_dwordx4 v[208:209], off
	v_lshl_add_u64 v[208:209], s[30:31], 0, v[162:163]
	s_mov_b32 m0, s6
	s_nop 0
	global_load_lds_dwordx4 v[208:209], off
	v_lshl_add_u64 v[208:209], s[30:31], 0, v[158:159]
	s_add_i32 m0, s6, 0x2000
	s_nop 0
	global_load_lds_dwordx4 v[208:209], off
	v_lshl_add_u64 v[208:209], v[212:213], 0, s[74:75]
	s_mov_b32 m0, s85
	s_nop 0
	global_load_lds_dwordx4 v[208:209], off
	v_lshl_add_u64 v[208:209], v[214:215], 0, s[74:75]
	s_mov_b32 m0, s86
	s_nop 0
	global_load_lds_dwordx4 v[208:209], off
	s_waitcnt vmcnt(8)
	s_waitcnt lgkmcnt(0)
	s_barrier
	s_setprio 1
	s_waitcnt lgkmcnt(0)
	v_mfma_f32_16x16x32_bf16 v[62:65], v[66:69], v[174:177], v[62:65]
	v_mfma_f32_16x16x32_bf16 v[58:61], v[74:77], v[174:177], v[58:61]
	v_mfma_f32_16x16x32_bf16 v[46:49], v[66:69], v[182:185], v[46:49]
	v_mfma_f32_16x16x32_bf16 v[42:45], v[74:77], v[182:185], v[42:45]
	v_mfma_f32_16x16x32_bf16 v[30:33], v[66:69], v[190:193], v[30:33]
	v_mfma_f32_16x16x32_bf16 v[26:29], v[74:77], v[190:193], v[26:29]
	v_mfma_f32_16x16x32_bf16 v[14:17], v[66:69], v[200:203], v[14:17]
	v_mfma_f32_16x16x32_bf16 v[10:13], v[74:77], v[200:203], v[10:13]
	v_mfma_f32_16x16x32_bf16 v[62:65], v[70:73], v[178:181], v[62:65]
	v_mfma_f32_16x16x32_bf16 v[58:61], v[78:81], v[178:181], v[58:61]
	v_mfma_f32_16x16x32_bf16 v[46:49], v[70:73], v[186:189], v[46:49]
	v_mfma_f32_16x16x32_bf16 v[42:45], v[78:81], v[186:189], v[42:45]
	v_mfma_f32_16x16x32_bf16 v[30:33], v[70:73], v[194:197], v[30:33]
	v_mfma_f32_16x16x32_bf16 v[26:29], v[78:81], v[194:197], v[26:29]
	v_mfma_f32_16x16x32_bf16 v[14:17], v[70:73], v[204:207], v[14:17]
	v_mfma_f32_16x16x32_bf16 v[10:13], v[78:81], v[204:207], v[10:13]
	s_setprio 0
	s_setprio 1
	v_mfma_f32_16x16x32_bf16 v[54:57], v[146:149], v[174:177], v[54:57]
	v_mfma_f32_16x16x32_bf16 v[50:53], v[154:157], v[174:177], v[50:53]
	v_mfma_f32_16x16x32_bf16 v[38:41], v[146:149], v[182:185], v[38:41]
	v_mfma_f32_16x16x32_bf16 v[34:37], v[154:157], v[182:185], v[34:37]
	v_mfma_f32_16x16x32_bf16 v[22:25], v[146:149], v[190:193], v[22:25]
	v_mfma_f32_16x16x32_bf16 v[18:21], v[154:157], v[190:193], v[18:21]
	v_mfma_f32_16x16x32_bf16 v[6:9], v[146:149], v[200:203], v[6:9]
	v_mfma_f32_16x16x32_bf16 v[2:5], v[154:157], v[200:203], v[2:5]
	v_mfma_f32_16x16x32_bf16 v[54:57], v[150:153], v[178:181], v[54:57]
	v_mfma_f32_16x16x32_bf16 v[50:53], v[170:173], v[178:181], v[50:53]
	v_mfma_f32_16x16x32_bf16 v[38:41], v[150:153], v[186:189], v[38:41]
	v_mfma_f32_16x16x32_bf16 v[34:37], v[170:173], v[186:189], v[34:37]
	v_mfma_f32_16x16x32_bf16 v[22:25], v[150:153], v[194:197], v[22:25]
	v_mfma_f32_16x16x32_bf16 v[18:21], v[170:173], v[194:197], v[18:21]
	v_mfma_f32_16x16x32_bf16 v[6:9], v[150:153], v[204:207], v[6:9]
	v_mfma_f32_16x16x32_bf16 v[2:5], v[170:173], v[204:207], v[2:5]
	s_setprio 0
	s_barrier
	s_add_i32 s94, s94, 2
	s_add_u32 s10, s10, 0x100
	s_addc_u32 s11, s11, 0
	s_add_u32 s92, s92, 0x100
	s_addc_u32 s93, s93, 0
	s_cmp_gt_u32 s94, 61
	s_cbranch_scc0 .LBB0_1556
	s_and_b64 vcc, exec, s[18:19]
	s_cbranch_vccz .LBB0_1559
	s_barrier
